# v30: + gdn_prep forward-substitution LDS reads re-pipelined (ring of 5 buffers, waits re-derived)
# speedup vs baseline: 1.0578x; 1.0083x over previous
.LBB0_3018:
	s_or_b64 exec, exec, s[0:1]
	s_and_saveexec_b64 s[0:1], s[20:21]
	s_cbranch_execz .LBB0_2859
	s_waitcnt lgkmcnt(0)
	ds_read_b96 v[12:14], v21 offset:50688
	ds_read2_b32 v[8:9], v88 offset1:65
	ds_read_b128 v[234:237], v95
	ds_read_b128 v[240:243], v96
	ds_read_b128 v[244:247], v97
	ds_read_b128 v[248:251], v98
	ds_read_b128 v[252:255], v21 offset:50944
	v_add_u32_e32 v20, 0x400, v88
	ds_read2_b32 v[48:49], v20 offset0:4 offset1:69
	v_add_u32_e32 v43, 0x800, v88
	v_add_u32_e32 v60, 0xc00, v88
	s_waitcnt lgkmcnt(5)
	v_mul_f32_e32 v0, v8, v234
	v_mul_f32_e32 v1, v235, v9
	ds_read_b32 v9, v21 offset:50176
	s_waitcnt lgkmcnt(5)
	v_mul_f32_e32 v4, v0, v240
	v_mul_f32_e32 v5, v1, v241
	v_cndmask_b32_e64 v0, v0, v4, s[26:27]
	v_add_f32_e32 v8, 0, v0
	v_cndmask_b32_e64 v10, v1, v5, s[26:27]
	ds_read_b64 v[4:5], v21 offset:50432
	ds_read2_b32 v[0:1], v88 offset0:130 offset1:195
	s_waitcnt lgkmcnt(2)
	v_fma_f32 v9, -v8, v9, v10
	s_waitcnt lgkmcnt(0)
	v_mul_f32_e32 v0, v236, v0
	v_mul_f32_e32 v2, v0, v242
	v_add_f32_e32 v9, 0, v9
	v_cndmask_b32_e64 v0, v0, v2, s[26:27]
	v_fma_f32 v0, -v8, v4, v0
	v_fma_f32 v2, -v9, v5, 0
	v_add_f32_e32 v10, v0, v2
	v_mul_f32_e32 v0, v237, v1
	ds_read_b128 v[234:237], v21 offset:51200
	v_mul_f32_e32 v1, v0, v243
	ds_read_b128 v[240:243], v21 offset:51456
	v_cndmask_b32_e64 v0, v0, v1, s[26:27]
	v_fma_f32 v11, -v8, v12, v0
	v_fma_f32 v12, -v9, v13, 0
	v_fma_f32 v13, -v10, v14, 0
	v_add_f32_e32 v11, v11, v12
	v_add_f32_e32 v11, v11, v13
	v_mul_f32_e32 v0, v48, v244
	v_mul_f32_e32 v4, v0, v248
	v_cndmask_b32_e64 v0, v0, v4, s[26:27]
	v_fma_f32 v0, -v8, v252, v0
	v_fma_f32 v4, -v9, v253, 0
	v_fma_f32 v12, -v10, v254, 0
	v_fma_f32 v13, -v11, v255, 0
	ds_read_b128 v[252:255], v21 offset:51712
	v_add_f32_e32 v0, v0, v4
	v_add_f32_e32 v4, v12, v13
	ds_read_b32 v13, v21 offset:51216
	v_add_f32_e32 v12, v0, v4
	v_mul_f32_e32 v0, v245, v49
	v_mul_f32_e32 v1, v0, v249
	v_cndmask_b32_e64 v0, v0, v1, s[26:27]
	s_waitcnt lgkmcnt(3)
	v_fma_f32 v4, -v8, v234, v0
	ds_read2_b32 v[0:1], v20 offset0:134 offset1:199
	v_fma_f32 v5, -v9, v235, 0
	v_fma_f32 v14, -v10, v236, 0
	v_fma_f32 v15, -v11, v237, 0
	ds_read_b128 v[234:237], v99
	s_waitcnt lgkmcnt(2)
	v_fma_f32 v4, -v12, v13, v4
	v_add_f32_e32 v4, v5, v4
	v_add_f32_e32 v5, v14, v15
	ds_read2_b32 v[52:53], v43 offset0:8 offset1:73
	v_add_f32_e32 v13, v5, v4
	ds_read_b64 v[4:5], v21 offset:51472
	s_waitcnt lgkmcnt(3)
	v_mul_f32_e32 v0, v246, v0
	v_mul_f32_e32 v2, v0, v250
	v_cndmask_b32_e64 v0, v0, v2, s[26:27]
	v_fma_f32 v0, -v8, v240, v0
	v_fma_f32 v2, -v9, v241, 0
	v_fma_f32 v6, -v10, v242, 0
	v_fma_f32 v14, -v11, v243, 0
	ds_read_b128 v[240:243], v100
	s_waitcnt lgkmcnt(1)
	v_fma_f32 v0, -v12, v4, v0
	v_fma_f32 v2, -v13, v5, v2
	v_add_f32_e32 v0, v0, v2
	v_add_f32_e32 v2, v6, v14
	v_add_f32_e32 v14, v2, v0
	v_mul_f32_e32 v0, v247, v1
	ds_read_b128 v[244:247], v21 offset:51968
	v_mul_f32_e32 v1, v0, v251
	ds_read_b128 v[248:251], v21 offset:51984
	v_cndmask_b32_e64 v3, v0, v1, s[26:27]
	ds_read_b96 v[0:2], v21 offset:51728
	v_fma_f32 v3, -v8, v252, v3
	v_fma_f32 v4, -v9, v253, 0
	v_fma_f32 v5, -v10, v254, 0
	s_waitcnt lgkmcnt(0)
	v_fma_f32 v0, -v12, v0, v3
	v_fma_f32 v1, -v13, v1, v4
	v_fma_f32 v20, -v14, v2, v5
	ds_read_b32 v49, v21 offset:52256
	v_add_f32_e32 v41, v0, v1
	v_fma_f32 v15, -v11, v255, 0
	ds_read_b128 v[252:255], v21 offset:52224
	v_mul_f32_e32 v0, v52, v234
	v_mul_f32_e32 v4, v0, v240
	v_add_f32_e32 v15, v15, v20
	v_cndmask_b32_e64 v0, v0, v4, s[26:27]
	v_add_f32_e32 v15, v41, v15
	v_fma_f32 v0, -v8, v244, v0
	v_fma_f32 v4, -v9, v245, 0
	v_fma_f32 v20, -v10, v246, 0
	v_fma_f32 v41, -v11, v247, 0
	ds_read_b128 v[244:247], v21 offset:52240
	v_fma_f32 v0, -v12, v248, v0
	v_fma_f32 v4, -v13, v249, v4
	v_fma_f32 v20, -v14, v250, v20
	v_fma_f32 v41, -v15, v251, v41
	ds_read_b128 v[248:251], v21 offset:52480
	v_add_f32_e32 v0, v0, v4
	v_add_f32_e32 v4, v20, v41
	v_add_f32_e32 v41, v0, v4
	v_mul_f32_e32 v0, v235, v53
	v_mul_f32_e32 v1, v0, v241
	v_cndmask_b32_e64 v0, v0, v1, s[26:27]
	s_waitcnt lgkmcnt(2)
	v_fma_f32 v0, -v8, v252, v0
	v_fma_f32 v1, -v9, v253, 0
	s_waitcnt lgkmcnt(1)
	v_fma_f32 v20, -v12, v244, v0
	v_fma_f32 v48, -v13, v245, v1
	ds_read2_b32 v[0:1], v43 offset0:138 offset1:203
	v_fma_f32 v4, -v10, v254, 0
	v_fma_f32 v5, -v11, v255, 0
	ds_read_b128 v[252:255], v21 offset:52496
	v_fma_f32 v4, -v14, v246, v4
	v_fma_f32 v5, -v15, v247, v5
	ds_read_b128 v[244:247], v21 offset:52736
	v_fma_f32 v20, -v41, v49, v20
	v_add_f32_e32 v20, v48, v20
	v_add_f32_e32 v4, v4, v5
	v_add_f32_e32 v43, v4, v20
	ds_read_b64 v[4:5], v21 offset:52512
	s_waitcnt lgkmcnt(3)
	v_mul_f32_e32 v0, v236, v0
	v_mul_f32_e32 v2, v0, v242
	v_cndmask_b32_e64 v0, v0, v2, s[26:27]
	v_fma_f32 v0, -v8, v248, v0
	v_fma_f32 v2, -v9, v249, 0
	v_fma_f32 v6, -v10, v250, 0
	v_fma_f32 v20, -v11, v251, 0
	ds_read_b128 v[248:251], v21 offset:52752
	s_waitcnt lgkmcnt(3)
	v_fma_f32 v0, -v12, v252, v0
	ds_read2_b32 v[58:59], v60 offset0:12 offset1:77
	v_fma_f32 v2, -v13, v253, v2
	v_fma_f32 v6, -v14, v254, v6
	v_fma_f32 v20, -v15, v255, v20
	ds_read_b128 v[252:255], v101
	s_waitcnt lgkmcnt(3)
	v_fma_f32 v0, -v41, v4, v0
	v_fma_f32 v2, -v43, v5, v2
	v_add_f32_e32 v0, v0, v2
	v_add_f32_e32 v2, v6, v20
	v_add_f32_e32 v44, v2, v0
	v_mul_f32_e32 v0, v237, v1
	ds_read_b128 v[234:237], v102
	v_mul_f32_e32 v1, v0, v243
	ds_read_b128 v[240:243], v21 offset:52992
	v_cndmask_b32_e64 v4, v0, v1, s[26:27]
	v_fma_f32 v7, -v8, v244, v4
	ds_read_b96 v[4:6], v21 offset:52768
	v_fma_f32 v20, -v9, v245, 0
	v_fma_f32 v45, -v10, v246, 0
	v_fma_f32 v46, -v11, v247, 0
	ds_read_b128 v[244:247], v21 offset:53008
	s_waitcnt lgkmcnt(6)
	v_fma_f32 v0, -v12, v248, v7
	v_fma_f32 v1, -v13, v249, v20
	v_fma_f32 v2, -v14, v250, v45
	v_fma_f32 v20, -v15, v251, v46
	ds_read_b128 v[248:251], v21 offset:53024
	s_waitcnt lgkmcnt(2)
	v_fma_f32 v4, -v41, v4, v0
	v_fma_f32 v5, -v43, v5, v1
	v_fma_f32 v45, -v44, v6, v2
	v_add_f32_e32 v46, v4, v5
	v_add_f32_e32 v20, v20, v45
	v_add_f32_e32 v45, v46, v20
	v_mul_f32_e32 v0, v58, v252
	v_mul_f32_e32 v4, v0, v234
	ds_read_b32 v52, v21 offset:53296
	v_cndmask_b32_e64 v0, v0, v4, s[26:27]
	v_fma_f32 v0, -v8, v240, v0
	v_fma_f32 v4, -v9, v241, 0
	v_fma_f32 v20, -v10, v242, 0
	v_fma_f32 v46, -v11, v243, 0
	ds_read_b128 v[240:243], v21 offset:53248
	s_waitcnt lgkmcnt(3)
	v_fma_f32 v0, -v12, v244, v0
	v_fma_f32 v4, -v13, v245, v4
	v_fma_f32 v20, -v14, v246, v20
	v_fma_f32 v46, -v15, v247, v46
	ds_read_b128 v[244:247], v21 offset:53264
	s_waitcnt lgkmcnt(3)
	v_fma_f32 v0, -v41, v248, v0
	v_fma_f32 v4, -v43, v249, v4
	v_fma_f32 v20, -v44, v250, v20
	v_fma_f32 v46, -v45, v251, v46
	ds_read_b128 v[248:251], v21 offset:53280
	v_add_f32_e32 v0, v0, v4
	v_add_f32_e32 v4, v20, v46
	v_add_f32_e32 v46, v0, v4
	v_mul_f32_e32 v0, v253, v59
	v_mul_f32_e32 v1, v0, v235
	v_cndmask_b32_e64 v0, v0, v1, s[26:27]
	s_waitcnt lgkmcnt(2)
	v_fma_f32 v0, -v8, v240, v0
	v_fma_f32 v1, -v9, v241, 0
	v_fma_f32 v4, -v10, v242, 0
	v_fma_f32 v5, -v11, v243, 0
	ds_read_b128 v[240:243], v21 offset:53504
	s_waitcnt lgkmcnt(2)
	v_fma_f32 v0, -v12, v244, v0
	v_fma_f32 v1, -v13, v245, v1
	v_fma_f32 v4, -v14, v246, v4
	v_fma_f32 v5, -v15, v247, v5
	ds_read_b128 v[244:247], v21 offset:53520
	s_waitcnt lgkmcnt(2)
	v_fma_f32 v20, -v41, v248, v0
	v_fma_f32 v47, -v43, v249, v1
	ds_read2_b32 v[0:1], v60 offset0:142 offset1:207
	v_fma_f32 v4, -v44, v250, v4
	v_fma_f32 v5, -v45, v251, v5
	ds_read_b128 v[248:251], v21 offset:53536
	v_fma_f32 v20, -v46, v52, v20
	v_add_f32_e32 v20, v47, v20
	s_waitcnt lgkmcnt(1)
	v_mul_f32_e32 v0, v254, v0
	v_mul_f32_e32 v2, v0, v236
	v_add_f32_e32 v4, v4, v5
	v_cndmask_b32_e64 v0, v0, v2, s[26:27]
	v_add_f32_e32 v47, v4, v20
	v_fma_f32 v0, -v8, v240, v0
	v_fma_f32 v2, -v9, v241, 0
	v_fma_f32 v4, -v10, v242, 0
	v_fma_f32 v5, -v11, v243, 0
	ds_read_b128 v[240:243], v21 offset:53760
	v_fma_f32 v6, -v14, v246, v4
	v_fma_f32 v20, -v15, v247, v5
	ds_read_b64 v[4:5], v21 offset:53552
	v_fma_f32 v0, -v12, v244, v0
	v_fma_f32 v2, -v13, v245, v2
	ds_read_b128 v[244:247], v21 offset:53776
	s_waitcnt lgkmcnt(3)
	v_fma_f32 v0, -v41, v248, v0
	v_fma_f32 v2, -v43, v249, v2
	v_fma_f32 v6, -v44, v250, v6
	v_fma_f32 v20, -v45, v251, v20
	ds_read_b128 v[248:251], v21 offset:53792
	s_waitcnt lgkmcnt(2)
	v_fma_f32 v0, -v46, v4, v0
	v_fma_f32 v2, -v47, v5, v2
	v_add_f32_e32 v0, v0, v2
	v_add_f32_e32 v2, v6, v20
	v_add_f32_e32 v48, v2, v0
	v_mul_f32_e32 v0, v255, v1
	ds_read_b128 v[252:255], v103
	ds_read_b128 v[62:65], v21 offset:54064
	v_mul_f32_e32 v1, v0, v237
	ds_read_b128 v[234:237], v104
	v_cndmask_b32_e64 v0, v0, v1, s[26:27]
	v_fma_f32 v20, -v8, v240, v0
	ds_read_b96 v[0:2], v21 offset:53808
	v_fma_f32 v49, -v9, v241, 0
	v_fma_f32 v50, -v10, v242, 0
	v_fma_f32 v51, -v11, v243, 0
	ds_read_b128 v[240:243], v21 offset:54016
	s_waitcnt lgkmcnt(6)
	v_fma_f32 v20, -v12, v244, v20
	v_fma_f32 v49, -v13, v245, v49
	v_fma_f32 v50, -v14, v246, v50
	v_fma_f32 v3, -v15, v247, v51
	ds_read_b128 v[244:247], v21 offset:54032
	s_waitcnt lgkmcnt(6)
	v_fma_f32 v4, -v41, v248, v20
	v_fma_f32 v5, -v43, v249, v49
	v_fma_f32 v6, -v44, v250, v50
	v_add_u32_e32 v68, 0x1000, v88
	ds_read2_b32 v[66:67], v68 offset0:16 offset1:81
	v_fma_f32 v20, -v45, v251, v3
	ds_read_b128 v[248:251], v21 offset:54048
	s_waitcnt lgkmcnt(4)
	v_fma_f32 v49, -v46, v0, v4
	v_fma_f32 v50, -v47, v1, v5
	v_fma_f32 v51, -v48, v2, v6
	v_add_f32_e32 v49, v49, v50
	v_add_f32_e32 v20, v20, v51
	s_waitcnt lgkmcnt(1)
	v_mul_f32_e32 v0, v66, v252
	v_mul_f32_e32 v4, v0, v234
	v_cndmask_b32_e64 v0, v0, v4, s[26:27]
	v_add_f32_e32 v49, v49, v20
	v_fma_f32 v0, -v8, v240, v0
	v_fma_f32 v4, -v9, v241, 0
	v_fma_f32 v20, -v10, v242, 0
	v_fma_f32 v50, -v11, v243, 0
	ds_read_b128 v[240:243], v21 offset:54272
	v_fma_f32 v0, -v12, v244, v0
	v_fma_f32 v4, -v13, v245, v4
	v_fma_f32 v20, -v14, v246, v20
	v_fma_f32 v50, -v15, v247, v50
	ds_read_b128 v[244:247], v21 offset:54288
	s_waitcnt lgkmcnt(2)
	v_fma_f32 v0, -v41, v248, v0
	v_fma_f32 v4, -v43, v249, v4
	v_fma_f32 v20, -v44, v250, v20
	v_fma_f32 v50, -v45, v251, v50
	ds_read_b32 v56, v21 offset:54336
	ds_read_b128 v[248:251], v21 offset:54304
	v_fma_f32 v0, -v46, v62, v0
	v_fma_f32 v4, -v47, v63, v4
	v_fma_f32 v20, -v48, v64, v20
	v_fma_f32 v50, -v49, v65, v50
	v_add_f32_e32 v0, v0, v4
	v_add_f32_e32 v4, v20, v50
	v_add_f32_e32 v50, v0, v4
	v_mul_f32_e32 v0, v253, v67
	v_mul_f32_e32 v1, v0, v235
	v_cndmask_b32_e64 v0, v0, v1, s[26:27]
	s_waitcnt lgkmcnt(3)
	v_fma_f32 v0, -v8, v240, v0
	v_fma_f32 v1, -v9, v241, 0
	v_fma_f32 v4, -v10, v242, 0
	v_fma_f32 v5, -v11, v243, 0
	ds_read_b128 v[240:243], v21 offset:54320
	s_waitcnt lgkmcnt(3)
	v_fma_f32 v0, -v12, v244, v0
	v_fma_f32 v1, -v13, v245, v1
	v_fma_f32 v4, -v14, v246, v4
	v_fma_f32 v5, -v15, v247, v5
	ds_read_b128 v[244:247], v21 offset:54528
	s_waitcnt lgkmcnt(2)
	v_fma_f32 v0, -v41, v248, v0
	v_fma_f32 v1, -v43, v249, v1
	v_fma_f32 v4, -v44, v250, v4
	v_fma_f32 v5, -v45, v251, v5
	ds_read_b128 v[248:251], v21 offset:54544
	s_waitcnt lgkmcnt(2)
	v_fma_f32 v20, -v46, v240, v0
	v_fma_f32 v51, -v47, v241, v1
	ds_read2_b32 v[0:1], v68 offset0:146 offset1:211
	v_fma_f32 v4, -v48, v242, v4
	v_fma_f32 v5, -v49, v243, v5
	ds_read_b128 v[240:243], v21 offset:54560
	v_add_f32_e32 v4, v4, v5
	s_waitcnt lgkmcnt(1)
	v_mul_f32_e32 v0, v254, v0
	v_fma_f32 v20, -v50, v56, v20
	v_mul_f32_e32 v2, v0, v236
	v_add_f32_e32 v20, v51, v20
	v_cndmask_b32_e64 v0, v0, v2, s[26:27]
	v_add_f32_e32 v51, v4, v20
	v_fma_f32 v0, -v8, v244, v0
	v_fma_f32 v2, -v9, v245, 0
	v_fma_f32 v4, -v10, v246, 0
	v_fma_f32 v5, -v11, v247, 0
	ds_read_b128 v[244:247], v21 offset:54576
	v_fma_f32 v0, -v12, v248, v0
	v_fma_f32 v2, -v13, v249, v2
	v_fma_f32 v4, -v14, v250, v4
	v_fma_f32 v5, -v15, v251, v5
	ds_read_b128 v[248:251], v21 offset:54784
	s_waitcnt lgkmcnt(2)
	v_fma_f32 v6, -v44, v242, v4
	v_fma_f32 v20, -v45, v243, v5
	ds_read_b64 v[4:5], v21 offset:54592
	v_fma_f32 v0, -v41, v240, v0
	v_fma_f32 v2, -v43, v241, v2
	ds_read_b128 v[240:243], v21 offset:54800
	s_waitcnt lgkmcnt(3)
	v_fma_f32 v0, -v46, v244, v0
	v_fma_f32 v2, -v47, v245, v2
	v_fma_f32 v6, -v48, v246, v6
	v_fma_f32 v20, -v49, v247, v20
	ds_read_b128 v[244:247], v21 offset:54816
	s_waitcnt lgkmcnt(2)
	v_fma_f32 v0, -v50, v4, v0
	v_fma_f32 v2, -v51, v5, v2
	v_add_f32_e32 v0, v0, v2
	v_add_f32_e32 v2, v6, v20
	v_add_f32_e32 v52, v2, v0
	v_mul_f32_e32 v0, v255, v1
	ds_read_b128 v[252:255], v21 offset:54832
	v_mul_f32_e32 v1, v0, v237
	ds_read_b128 v[234:237], v105
	v_cndmask_b32_e64 v4, v0, v1, s[26:27]
	v_add_u32_e32 v186, 0x1400, v88
	ds_read2_b32 v[184:185], v186 offset0:20 offset1:85
	ds_read_b128 v[66:69], v21 offset:55088
	v_fma_f32 v4, -v8, v248, v4
	v_fma_f32 v20, -v9, v249, 0
	v_fma_f32 v53, -v10, v250, 0
	s_waitcnt lgkmcnt(5)
	v_fma_f32 v55, -v12, v240, v4
	ds_read_b96 v[4:6], v21 offset:54848
	v_fma_f32 v54, -v11, v251, 0
	ds_read_b128 v[248:251], v106
	v_fma_f32 v20, -v13, v241, v20
	v_fma_f32 v53, -v14, v242, v53
	v_fma_f32 v54, -v15, v243, v54
	ds_read_b128 v[240:243], v21 offset:55040
	s_waitcnt lgkmcnt(7)
	v_fma_f32 v55, -v41, v244, v55
	v_fma_f32 v20, -v43, v245, v20
	v_fma_f32 v53, -v44, v246, v53
	v_fma_f32 v7, -v45, v247, v54
	ds_read_b128 v[244:247], v21 offset:55056
	s_waitcnt lgkmcnt(7)
	v_fma_f32 v0, -v46, v252, v55
	v_fma_f32 v1, -v47, v253, v20
	v_fma_f32 v2, -v48, v254, v53
	v_fma_f32 v20, -v49, v255, v7
	ds_read_b128 v[252:255], v21 offset:55072
	s_waitcnt lgkmcnt(4)
	v_fma_f32 v53, -v50, v4, v0
	v_fma_f32 v54, -v51, v5, v1
	v_fma_f32 v55, -v52, v6, v2
	v_add_f32_e32 v53, v53, v54
	v_add_f32_e32 v20, v20, v55
	v_mul_f32_e32 v0, v184, v234
	s_waitcnt lgkmcnt(3)
	v_mul_f32_e32 v4, v0, v248
	v_cndmask_b32_e64 v0, v0, v4, s[26:27]
	s_waitcnt lgkmcnt(2)
	v_fma_f32 v0, -v8, v240, v0
	v_fma_f32 v54, -v11, v243, 0
	s_waitcnt lgkmcnt(1)
	v_fma_f32 v54, -v15, v247, v54
	v_add_f32_e32 v53, v53, v20
	v_fma_f32 v4, -v9, v241, 0
	v_fma_f32 v20, -v10, v242, 0
	ds_read_b128 v[240:243], v21 offset:55104
	v_fma_f32 v0, -v12, v244, v0
	s_waitcnt lgkmcnt(1)
	v_fma_f32 v58, -v45, v255, v54
	v_fma_f32 v4, -v13, v245, v4
	v_fma_f32 v20, -v14, v246, v20
	ds_read_b128 v[244:247], v21 offset:55296
	v_fma_f32 v0, -v41, v252, v0
	v_fma_f32 v4, -v43, v253, v4
	v_fma_f32 v20, -v44, v254, v20
	ds_read_b128 v[252:255], v21 offset:55312
	v_fma_f32 v0, -v46, v66, v0
	v_fma_f32 v4, -v47, v67, v4
	v_fma_f32 v20, -v48, v68, v20
	ds_read_b32 v60, v21 offset:55376
	v_fma_f32 v62, -v49, v69, v58
	s_waitcnt lgkmcnt(3)
	v_fma_f32 v0, -v50, v240, v0
	v_fma_f32 v4, -v51, v241, v4
	v_fma_f32 v20, -v52, v242, v20
	v_fma_f32 v54, -v53, v243, v62
	ds_read_b128 v[240:243], v21 offset:55328
	v_add_f32_e32 v0, v0, v4
	v_add_f32_e32 v4, v20, v54
	v_add_f32_e32 v54, v0, v4
	v_mul_f32_e32 v0, v235, v185
	v_mul_f32_e32 v1, v0, v249
	v_cndmask_b32_e64 v0, v0, v1, s[26:27]
	s_waitcnt lgkmcnt(3)
	v_fma_f32 v0, -v8, v244, v0
	v_fma_f32 v1, -v9, v245, 0
	v_fma_f32 v4, -v10, v246, 0
	v_fma_f32 v5, -v11, v247, 0
	ds_read_b128 v[244:247], v21 offset:55344
	s_waitcnt lgkmcnt(3)
	v_fma_f32 v0, -v12, v252, v0
	v_fma_f32 v1, -v13, v253, v1
	v_fma_f32 v4, -v14, v254, v4
	v_fma_f32 v5, -v15, v255, v5
	ds_read_b128 v[252:255], v21 offset:55360
	s_waitcnt lgkmcnt(2)
	v_fma_f32 v0, -v41, v240, v0
	v_fma_f32 v1, -v43, v241, v1
	v_fma_f32 v4, -v44, v242, v4
	v_fma_f32 v5, -v45, v243, v5
	ds_read_b128 v[240:243], v21 offset:55552
	s_waitcnt lgkmcnt(2)
	v_fma_f32 v0, -v46, v244, v0
	v_fma_f32 v1, -v47, v245, v1
	v_fma_f32 v4, -v48, v246, v4
	v_fma_f32 v5, -v49, v247, v5
	ds_read_b128 v[244:247], v21 offset:55568
	s_waitcnt lgkmcnt(2)
	v_fma_f32 v20, -v50, v252, v0
	v_fma_f32 v55, -v51, v253, v1
	ds_read2_b32 v[0:1], v186 offset0:150 offset1:215
	v_fma_f32 v4, -v52, v254, v4
	v_fma_f32 v5, -v53, v255, v5
	ds_read_b128 v[252:255], v21 offset:55584
	v_fma_f32 v20, -v54, v60, v20
	v_add_f32_e32 v20, v55, v20
	s_waitcnt lgkmcnt(1)
	v_mul_f32_e32 v0, v236, v0
	v_mul_f32_e32 v2, v0, v250
	v_add_f32_e32 v4, v4, v5
	v_cndmask_b32_e64 v0, v0, v2, s[26:27]
	v_add_f32_e32 v55, v4, v20
	v_fma_f32 v0, -v8, v240, v0
	v_fma_f32 v2, -v9, v241, 0
	v_fma_f32 v4, -v10, v242, 0
	v_fma_f32 v5, -v11, v243, 0
	ds_read_b128 v[240:243], v21 offset:55600
	v_fma_f32 v0, -v12, v244, v0
	v_fma_f32 v2, -v13, v245, v2
	v_fma_f32 v4, -v14, v246, v4
	v_fma_f32 v5, -v15, v247, v5
	ds_read_b128 v[244:247], v21 offset:55616
	s_waitcnt lgkmcnt(2)
	v_fma_f32 v0, -v41, v252, v0
	v_fma_f32 v2, -v43, v253, v2
	v_fma_f32 v4, -v44, v254, v4
	v_fma_f32 v5, -v45, v255, v5
	ds_read_b128 v[252:255], v21 offset:55808
	s_waitcnt lgkmcnt(2)
	v_fma_f32 v6, -v48, v242, v4
	v_fma_f32 v20, -v49, v243, v5
	ds_read_b64 v[4:5], v21 offset:55632
	v_fma_f32 v0, -v46, v240, v0
	v_fma_f32 v2, -v47, v241, v2
	ds_read_b128 v[240:243], v21 offset:55824
	s_waitcnt lgkmcnt(3)
	v_fma_f32 v0, -v50, v244, v0
	v_fma_f32 v2, -v51, v245, v2
	v_fma_f32 v6, -v52, v246, v6
	v_fma_f32 v20, -v53, v247, v20
	ds_read_b128 v[244:247], v21 offset:55840
	s_waitcnt lgkmcnt(2)
	v_fma_f32 v0, -v54, v4, v0
	v_fma_f32 v2, -v55, v5, v2
	v_add_f32_e32 v0, v0, v2
	v_add_f32_e32 v2, v6, v20
	v_add_f32_e32 v56, v2, v0
	v_mul_f32_e32 v0, v237, v1
	ds_read_b128 v[234:237], v21 offset:55856
	v_mul_f32_e32 v1, v0, v251
	ds_read_b128 v[248:251], v21 offset:55872
	v_cndmask_b32_e64 v0, v0, v1, s[26:27]
	v_fma_f32 v20, -v8, v252, v0
	v_fma_f32 v57, -v9, v253, 0
	v_fma_f32 v58, -v10, v254, 0
	v_fma_f32 v59, -v11, v255, 0
	ds_read_b128 v[252:255], v107
	s_waitcnt lgkmcnt(4)
	v_fma_f32 v0, -v12, v240, v20
	v_fma_f32 v20, -v13, v241, v57
	ds_read_b128 v[184:187], v21 offset:56112
	v_fma_f32 v57, -v14, v242, v58
	v_fma_f32 v58, -v15, v243, v59
	ds_read_b128 v[240:243], v108
	s_waitcnt lgkmcnt(5)
	v_fma_f32 v59, -v41, v244, v0
	ds_read_b96 v[0:2], v21 offset:55888
	v_fma_f32 v20, -v43, v245, v20
	v_fma_f32 v57, -v44, v246, v57
	v_fma_f32 v58, -v45, v247, v58
	ds_read_b128 v[244:247], v21 offset:56064
	s_waitcnt lgkmcnt(6)
	v_fma_f32 v59, -v46, v234, v59
	v_fma_f32 v20, -v47, v235, v20
	v_fma_f32 v57, -v48, v236, v57
	v_fma_f32 v3, -v49, v237, v58
	ds_read_b128 v[234:237], v21 offset:56080
	s_waitcnt lgkmcnt(6)
	v_fma_f32 v4, -v50, v248, v59
	v_fma_f32 v5, -v51, v249, v20
	v_fma_f32 v6, -v52, v250, v57
	v_add_u32_e32 v190, 0x1800, v88
	ds_read2_b32 v[188:189], v190 offset0:24 offset1:89
	v_fma_f32 v20, -v53, v251, v3
	ds_read_b128 v[248:251], v21 offset:56096
	s_waitcnt lgkmcnt(4)
	v_fma_f32 v57, -v54, v0, v4
	v_fma_f32 v58, -v55, v1, v5
	v_fma_f32 v59, -v56, v2, v6
	v_add_f32_e32 v57, v57, v58
	v_add_f32_e32 v20, v20, v59
	s_waitcnt lgkmcnt(1)
	v_mul_f32_e32 v0, v188, v252
	v_mul_f32_e32 v4, v0, v240
	v_cndmask_b32_e64 v0, v0, v4, s[26:27]
	v_fma_f32 v0, -v8, v244, v0
	v_fma_f32 v58, -v11, v247, 0
	v_fma_f32 v58, -v15, v237, v58
	v_add_f32_e32 v57, v57, v20
	v_fma_f32 v4, -v9, v245, 0
	v_fma_f32 v20, -v10, v246, 0
	ds_read_b128 v[244:247], v21 offset:56128
	v_fma_f32 v0, -v12, v234, v0
	s_waitcnt lgkmcnt(1)
	v_fma_f32 v62, -v45, v251, v58
	v_fma_f32 v4, -v13, v235, v4
	v_fma_f32 v20, -v14, v236, v20
	ds_read_b128 v[234:237], v21 offset:56144
	v_fma_f32 v0, -v41, v248, v0
	v_fma_f32 v66, -v49, v187, v62
	v_fma_f32 v4, -v43, v249, v4
	v_fma_f32 v20, -v44, v250, v20
	ds_read_b128 v[248:251], v21 offset:56320
	v_fma_f32 v0, -v46, v184, v0
	v_fma_f32 v4, -v47, v185, v4
	v_fma_f32 v20, -v48, v186, v20
	s_waitcnt lgkmcnt(2)
	v_fma_f32 v0, -v50, v244, v0
	v_fma_f32 v4, -v51, v245, v4
	v_fma_f32 v20, -v52, v246, v20
	v_fma_f32 v58, -v53, v247, v66
	ds_read_b128 v[244:247], v21 offset:56336
	s_waitcnt lgkmcnt(2)
	v_fma_f32 v0, -v54, v234, v0
	v_fma_f32 v4, -v55, v235, v4
	v_fma_f32 v20, -v56, v236, v20
	v_fma_f32 v58, -v57, v237, v58
	ds_read_b128 v[234:237], v21 offset:56352
	v_add_f32_e32 v0, v0, v4
	v_add_f32_e32 v4, v20, v58
	v_add_f32_e32 v58, v0, v4
	v_mul_f32_e32 v0, v253, v189
	v_mul_f32_e32 v1, v0, v241
	ds_read_b32 v64, v21 offset:56416
	v_cndmask_b32_e64 v0, v0, v1, s[26:27]
	s_waitcnt lgkmcnt(3)
	v_fma_f32 v0, -v8, v248, v0
	v_fma_f32 v1, -v9, v249, 0
	v_fma_f32 v4, -v10, v250, 0
	v_fma_f32 v5, -v11, v251, 0
	ds_read_b128 v[248:251], v21 offset:56368
	s_waitcnt lgkmcnt(3)
	v_fma_f32 v0, -v12, v244, v0
	v_fma_f32 v1, -v13, v245, v1
	v_fma_f32 v4, -v14, v246, v4
	v_fma_f32 v5, -v15, v247, v5
	ds_read_b128 v[244:247], v21 offset:56384
	s_waitcnt lgkmcnt(3)
	v_fma_f32 v0, -v41, v234, v0
	v_fma_f32 v1, -v43, v235, v1
	v_fma_f32 v4, -v44, v236, v4
	v_fma_f32 v5, -v45, v237, v5
	ds_read_b128 v[234:237], v21 offset:56400
	s_waitcnt lgkmcnt(2)
	v_fma_f32 v0, -v46, v248, v0
	v_fma_f32 v1, -v47, v249, v1
	v_fma_f32 v4, -v48, v250, v4
	v_fma_f32 v5, -v49, v251, v5
	ds_read_b128 v[248:251], v21 offset:56576
	s_waitcnt lgkmcnt(2)
	v_fma_f32 v0, -v50, v244, v0
	v_fma_f32 v1, -v51, v245, v1
	v_fma_f32 v4, -v52, v246, v4
	v_fma_f32 v5, -v53, v247, v5
	ds_read_b128 v[244:247], v21 offset:56592
	s_waitcnt lgkmcnt(2)
	v_fma_f32 v20, -v54, v234, v0
	v_fma_f32 v59, -v55, v235, v1
	ds_read2_b32 v[0:1], v190 offset0:154 offset1:219
	v_fma_f32 v4, -v56, v236, v4
	v_fma_f32 v5, -v57, v237, v5
	ds_read_b128 v[234:237], v21 offset:56608
	v_add_f32_e32 v4, v4, v5
	s_waitcnt lgkmcnt(1)
	v_mul_f32_e32 v0, v254, v0
	v_fma_f32 v20, -v58, v64, v20
	v_mul_f32_e32 v2, v0, v242
	v_add_f32_e32 v20, v59, v20
	v_cndmask_b32_e64 v0, v0, v2, s[26:27]
	v_add_f32_e32 v59, v4, v20
	v_fma_f32 v0, -v8, v248, v0
	v_fma_f32 v2, -v9, v249, 0
	v_fma_f32 v4, -v10, v250, 0
	v_fma_f32 v5, -v11, v251, 0
	ds_read_b128 v[248:251], v21 offset:56624
	v_fma_f32 v0, -v12, v244, v0
	v_fma_f32 v2, -v13, v245, v2
	v_fma_f32 v4, -v14, v246, v4
	v_fma_f32 v5, -v15, v247, v5
	ds_read_b128 v[244:247], v21 offset:56640
	s_waitcnt lgkmcnt(2)
	v_fma_f32 v0, -v41, v234, v0
	v_fma_f32 v2, -v43, v235, v2
	v_fma_f32 v4, -v44, v236, v4
	v_fma_f32 v5, -v45, v237, v5
	ds_read_b128 v[234:237], v21 offset:56656
	s_waitcnt lgkmcnt(2)
	v_fma_f32 v0, -v46, v248, v0
	v_fma_f32 v2, -v47, v249, v2
	v_fma_f32 v4, -v48, v250, v4
	v_fma_f32 v5, -v49, v251, v5
	ds_read_b128 v[248:251], v21 offset:56832
	s_waitcnt lgkmcnt(2)
	v_fma_f32 v6, -v52, v246, v4
	v_fma_f32 v20, -v53, v247, v5
	ds_read_b64 v[4:5], v21 offset:56672
	v_fma_f32 v0, -v50, v244, v0
	v_fma_f32 v2, -v51, v245, v2
	ds_read_b128 v[244:247], v21 offset:56848
	s_waitcnt lgkmcnt(3)
	v_fma_f32 v0, -v54, v234, v0
	v_fma_f32 v2, -v55, v235, v2
	v_fma_f32 v6, -v56, v236, v6
	v_fma_f32 v20, -v57, v237, v20
	ds_read_b128 v[234:237], v21 offset:56864
	s_waitcnt lgkmcnt(2)
	v_fma_f32 v0, -v58, v4, v0
	v_fma_f32 v2, -v59, v5, v2
	v_add_f32_e32 v0, v0, v2
	v_add_f32_e32 v2, v6, v20
	v_add_f32_e32 v60, v2, v0
	v_mul_f32_e32 v0, v255, v1
	ds_read_b128 v[252:255], v21 offset:56880
	v_mul_f32_e32 v1, v0, v243
	ds_read_b128 v[240:243], v21 offset:56896
	v_cndmask_b32_e64 v4, v0, v1, s[26:27]
	v_add_u32_e32 v194, 0x1c00, v88
	v_fma_f32 v4, -v8, v248, v4
	v_fma_f32 v20, -v9, v249, 0
	v_fma_f32 v61, -v10, v250, 0
	v_fma_f32 v62, -v11, v251, 0
	ds_read_b128 v[248:251], v21 offset:56912
	s_waitcnt lgkmcnt(4)
	v_fma_f32 v63, -v12, v244, v4
	ds_read2_b32 v[192:193], v194 offset0:28 offset1:93
	v_fma_f32 v20, -v13, v245, v20
	v_fma_f32 v61, -v14, v246, v61
	v_fma_f32 v62, -v15, v247, v62
	ds_read_b128 v[244:247], v109
	ds_read_b128 v[188:191], v21 offset:57136
	s_waitcnt lgkmcnt(6)
	v_fma_f32 v4, -v41, v234, v63
	v_fma_f32 v20, -v43, v235, v20
	v_fma_f32 v61, -v44, v236, v61
	v_fma_f32 v62, -v45, v237, v62
	ds_read_b128 v[234:237], v110
	s_waitcnt lgkmcnt(6)
	v_fma_f32 v63, -v46, v252, v4
	ds_read_b96 v[4:6], v21 offset:56928
	v_fma_f32 v20, -v47, v253, v20
	v_fma_f32 v61, -v48, v254, v61
	v_fma_f32 v62, -v49, v255, v62
	ds_read_b128 v[252:255], v21 offset:57088
	s_waitcnt lgkmcnt(7)
	v_fma_f32 v63, -v50, v240, v63
	v_fma_f32 v20, -v51, v241, v20
	v_fma_f32 v61, -v52, v242, v61
	v_fma_f32 v7, -v53, v243, v62
	ds_read_b128 v[240:243], v21 offset:57104
	s_waitcnt lgkmcnt(7)
	v_fma_f32 v0, -v54, v248, v63
	v_fma_f32 v1, -v55, v249, v20
	v_fma_f32 v2, -v56, v250, v61
	v_fma_f32 v20, -v57, v251, v7
	ds_read_b128 v[248:251], v21 offset:57120
	s_waitcnt lgkmcnt(3)
	v_fma_f32 v61, -v58, v4, v0
	v_fma_f32 v62, -v59, v5, v1
	v_fma_f32 v63, -v60, v6, v2
	v_add_f32_e32 v61, v61, v62
	v_add_f32_e32 v20, v20, v63
	v_mul_f32_e32 v0, v192, v244
	v_mul_f32_e32 v4, v0, v234
	v_cndmask_b32_e64 v0, v0, v4, s[26:27]
	s_waitcnt lgkmcnt(2)
	v_fma_f32 v0, -v8, v252, v0
	v_fma_f32 v62, -v11, v255, 0
	s_waitcnt lgkmcnt(1)
	v_fma_f32 v62, -v15, v243, v62
	v_add_f32_e32 v61, v61, v20
	v_fma_f32 v4, -v9, v253, 0
	v_fma_f32 v20, -v10, v254, 0
	ds_read_b128 v[252:255], v21 offset:57152
	v_fma_f32 v0, -v12, v240, v0
	s_waitcnt lgkmcnt(1)
	v_fma_f32 v66, -v45, v251, v62
	v_fma_f32 v4, -v13, v241, v4
	v_fma_f32 v20, -v14, v242, v20
	ds_read_b128 v[240:243], v21 offset:57168
	v_fma_f32 v0, -v41, v248, v0
	v_fma_f32 v4, -v43, v249, v4
	v_fma_f32 v20, -v44, v250, v20
	ds_read_b128 v[248:251], v21 offset:57184
	v_fma_f32 v0, -v46, v188, v0
	v_fma_f32 v4, -v47, v189, v4
	v_fma_f32 v20, -v48, v190, v20
	v_fma_f32 v184, -v49, v191, v66
	s_waitcnt lgkmcnt(2)
	v_fma_f32 v0, -v50, v252, v0
	v_fma_f32 v4, -v51, v253, v4
	v_fma_f32 v20, -v52, v254, v20
	v_fma_f32 v184, -v53, v255, v184
	ds_read_b128 v[252:255], v21 offset:57344
	s_waitcnt lgkmcnt(2)
	v_fma_f32 v0, -v54, v240, v0
	v_fma_f32 v4, -v55, v241, v4
	v_fma_f32 v20, -v56, v242, v20
	v_fma_f32 v184, -v57, v243, v184
	ds_read_b128 v[240:243], v21 offset:57360
	s_waitcnt lgkmcnt(2)
	v_fma_f32 v0, -v58, v248, v0
	v_fma_f32 v4, -v59, v249, v4
	v_fma_f32 v20, -v60, v250, v20
	v_fma_f32 v62, -v61, v251, v184
	ds_read_b128 v[248:251], v21 offset:57376
	v_add_f32_e32 v0, v0, v4
	v_add_f32_e32 v4, v20, v62
	v_add_f32_e32 v62, v0, v4
	v_mul_f32_e32 v0, v245, v193
	v_mul_f32_e32 v1, v0, v235
	v_cndmask_b32_e64 v0, v0, v1, s[26:27]
	s_waitcnt lgkmcnt(2)
	v_fma_f32 v0, -v8, v252, v0
	v_fma_f32 v1, -v9, v253, 0
	v_fma_f32 v4, -v10, v254, 0
	v_fma_f32 v5, -v11, v255, 0
	ds_read_b32 v68, v21 offset:57456
	ds_read_b128 v[252:255], v21 offset:57392
	s_waitcnt lgkmcnt(3)
	v_fma_f32 v0, -v12, v240, v0
	v_fma_f32 v1, -v13, v241, v1
	v_fma_f32 v4, -v14, v242, v4
	v_fma_f32 v5, -v15, v243, v5
	ds_read_b128 v[240:243], v21 offset:57408
	s_waitcnt lgkmcnt(3)
	v_fma_f32 v0, -v41, v248, v0
	v_fma_f32 v1, -v43, v249, v1
	v_fma_f32 v4, -v44, v250, v4
	v_fma_f32 v5, -v45, v251, v5
	ds_read_b128 v[248:251], v21 offset:57424
	s_waitcnt lgkmcnt(2)
	v_fma_f32 v0, -v46, v252, v0
	v_fma_f32 v1, -v47, v253, v1
	v_fma_f32 v4, -v48, v254, v4
	v_fma_f32 v5, -v49, v255, v5
	ds_read_b128 v[252:255], v21 offset:57440
	s_waitcnt lgkmcnt(2)
	v_fma_f32 v0, -v50, v240, v0
	v_fma_f32 v1, -v51, v241, v1
	v_fma_f32 v4, -v52, v242, v4
	v_fma_f32 v5, -v53, v243, v5
	ds_read_b128 v[240:243], v21 offset:57600
	s_waitcnt lgkmcnt(2)
	v_fma_f32 v0, -v54, v248, v0
	v_fma_f32 v1, -v55, v249, v1
	v_fma_f32 v4, -v56, v250, v4
	v_fma_f32 v5, -v57, v251, v5
	ds_read_b128 v[248:251], v21 offset:57616
	s_waitcnt lgkmcnt(2)
	v_fma_f32 v20, -v58, v252, v0
	v_fma_f32 v63, -v59, v253, v1
	ds_read2_b32 v[0:1], v194 offset0:158 offset1:223
	v_fma_f32 v4, -v60, v254, v4
	v_fma_f32 v5, -v61, v255, v5
	ds_read_b128 v[252:255], v21 offset:57632
	v_fma_f32 v20, -v62, v68, v20
	v_add_f32_e32 v20, v63, v20
	s_waitcnt lgkmcnt(1)
	v_mul_f32_e32 v0, v246, v0
	v_mul_f32_e32 v2, v0, v236
	v_add_f32_e32 v4, v4, v5
	v_cndmask_b32_e64 v0, v0, v2, s[26:27]
	v_add_f32_e32 v63, v4, v20
	v_fma_f32 v0, -v8, v240, v0
	v_fma_f32 v2, -v9, v241, 0
	v_fma_f32 v4, -v10, v242, 0
	v_fma_f32 v5, -v11, v243, 0
	ds_read_b128 v[240:243], v21 offset:57648
	v_fma_f32 v0, -v12, v248, v0
	v_fma_f32 v2, -v13, v249, v2
	v_fma_f32 v4, -v14, v250, v4
	v_fma_f32 v5, -v15, v251, v5
	ds_read_b128 v[248:251], v21 offset:57664
	s_waitcnt lgkmcnt(2)
	v_fma_f32 v0, -v41, v252, v0
	v_fma_f32 v2, -v43, v253, v2
	v_fma_f32 v4, -v44, v254, v4
	v_fma_f32 v5, -v45, v255, v5
	ds_read_b128 v[252:255], v21 offset:57680
	s_waitcnt lgkmcnt(2)
	v_fma_f32 v0, -v46, v240, v0
	v_fma_f32 v2, -v47, v241, v2
	v_fma_f32 v4, -v48, v242, v4
	v_fma_f32 v5, -v49, v243, v5
	ds_read_b128 v[240:243], v21 offset:57696
	s_waitcnt lgkmcnt(2)
	v_fma_f32 v0, -v50, v248, v0
	v_fma_f32 v2, -v51, v249, v2
	v_fma_f32 v4, -v52, v250, v4
	v_fma_f32 v5, -v53, v251, v5
	ds_read_b128 v[248:251], v21 offset:57856
	s_waitcnt lgkmcnt(2)
	v_fma_f32 v6, -v56, v254, v4
	v_fma_f32 v20, -v57, v255, v5
	ds_read_b64 v[4:5], v21 offset:57712
	v_fma_f32 v0, -v54, v252, v0
	v_fma_f32 v2, -v55, v253, v2
	ds_read_b128 v[252:255], v21 offset:57872
	s_waitcnt lgkmcnt(3)
	v_fma_f32 v0, -v58, v240, v0
	v_fma_f32 v2, -v59, v241, v2
	v_fma_f32 v6, -v60, v242, v6
	v_fma_f32 v20, -v61, v243, v20
	ds_read_b128 v[240:243], v21 offset:57888
	s_waitcnt lgkmcnt(2)
	v_fma_f32 v0, -v62, v4, v0
	v_fma_f32 v2, -v63, v5, v2
	v_add_f32_e32 v0, v0, v2
	v_add_f32_e32 v2, v6, v20
	v_add_f32_e32 v64, v2, v0
	v_mul_f32_e32 v0, v247, v1
	ds_read_b128 v[244:247], v21 offset:57904
	v_mul_f32_e32 v1, v0, v237
	ds_read_b128 v[234:237], v21 offset:57920
	v_cndmask_b32_e64 v0, v0, v1, s[26:27]
	v_fma_f32 v20, -v8, v248, v0
	v_fma_f32 v65, -v9, v249, 0
	v_fma_f32 v66, -v10, v250, 0
	v_fma_f32 v67, -v11, v251, 0
	ds_read_b128 v[248:251], v21 offset:57936
	s_waitcnt lgkmcnt(4)
	v_fma_f32 v0, -v12, v252, v20
	v_fma_f32 v20, -v13, v253, v65
	v_fma_f32 v65, -v14, v254, v66
	v_fma_f32 v66, -v15, v255, v67
	ds_read_b128 v[252:255], v21 offset:57952
	s_waitcnt lgkmcnt(4)
	v_fma_f32 v67, -v41, v240, v0
	v_fma_f32 v20, -v43, v241, v20
	v_fma_f32 v65, -v44, v242, v65
	v_fma_f32 v66, -v45, v243, v66
	ds_read_b128 v[240:243], v111
	s_waitcnt lgkmcnt(4)
	v_fma_f32 v0, -v46, v244, v67
	v_fma_f32 v20, -v47, v245, v20
	ds_read_b128 v[192:195], v21 offset:58160
	v_fma_f32 v65, -v48, v246, v65
	v_fma_f32 v66, -v49, v247, v66
	ds_read_b128 v[244:247], v112
	s_waitcnt lgkmcnt(5)
	v_fma_f32 v67, -v50, v234, v0
	ds_read_b96 v[0:2], v21 offset:57968
	v_fma_f32 v20, -v51, v235, v20
	v_fma_f32 v65, -v52, v236, v65
	v_fma_f32 v66, -v53, v237, v66
	ds_read_b128 v[234:237], v21 offset:58112
	s_waitcnt lgkmcnt(6)
	v_fma_f32 v67, -v54, v248, v67
	v_fma_f32 v20, -v55, v249, v20
	v_fma_f32 v65, -v56, v250, v65
	v_fma_f32 v3, -v57, v251, v66
	ds_read_b128 v[248:251], v21 offset:58128
	s_waitcnt lgkmcnt(6)
	v_fma_f32 v4, -v58, v252, v67
	v_fma_f32 v5, -v59, v253, v20
	v_fma_f32 v6, -v60, v254, v65
	v_add_u32_e32 v198, 0x2000, v88
	ds_read2_b32 v[196:197], v198 offset0:32 offset1:97
	v_fma_f32 v20, -v61, v255, v3
	ds_read_b128 v[252:255], v21 offset:58144
	s_waitcnt lgkmcnt(4)
	v_fma_f32 v65, -v62, v0, v4
	v_fma_f32 v66, -v63, v1, v5
	v_fma_f32 v67, -v64, v2, v6
	v_add_f32_e32 v65, v65, v66
	v_add_f32_e32 v20, v20, v67
	s_waitcnt lgkmcnt(1)
	v_mul_f32_e32 v0, v196, v240
	v_mul_f32_e32 v4, v0, v244
	v_cndmask_b32_e64 v0, v0, v4, s[26:27]
	v_fma_f32 v0, -v8, v234, v0
	v_fma_f32 v66, -v11, v237, 0
	v_fma_f32 v66, -v15, v251, v66
	v_add_f32_e32 v65, v65, v20
	v_fma_f32 v4, -v9, v235, 0
	v_fma_f32 v20, -v10, v236, 0
	ds_read_b128 v[234:237], v21 offset:58176
	v_fma_f32 v0, -v12, v248, v0
	s_waitcnt lgkmcnt(1)
	v_fma_f32 v184, -v45, v255, v66
	v_fma_f32 v4, -v13, v249, v4
	v_fma_f32 v20, -v14, v250, v20
	ds_read_b128 v[248:251], v21 offset:58192
	v_fma_f32 v0, -v41, v252, v0
	v_fma_f32 v188, -v49, v195, v184
	v_fma_f32 v4, -v43, v253, v4
	v_fma_f32 v20, -v44, v254, v20
	ds_read_b128 v[252:255], v21 offset:58208
	v_fma_f32 v0, -v46, v192, v0
	v_fma_f32 v4, -v47, v193, v4
	v_fma_f32 v20, -v48, v194, v20
	s_waitcnt lgkmcnt(2)
	v_fma_f32 v0, -v50, v234, v0
	v_fma_f32 v4, -v51, v235, v4
	v_fma_f32 v20, -v52, v236, v20
	v_fma_f32 v188, -v53, v237, v188
	ds_read_b128 v[234:237], v21 offset:58224
	s_waitcnt lgkmcnt(2)
	v_fma_f32 v0, -v54, v248, v0
	v_fma_f32 v4, -v55, v249, v4
	v_fma_f32 v20, -v56, v250, v20
	v_fma_f32 v188, -v57, v251, v188
	ds_read_b128 v[248:251], v21 offset:58368
	s_waitcnt lgkmcnt(2)
	v_fma_f32 v0, -v58, v252, v0
	v_fma_f32 v4, -v59, v253, v4
	v_fma_f32 v20, -v60, v254, v20
	v_fma_f32 v66, -v61, v255, v188
	ds_read_b128 v[252:255], v21 offset:58384
	s_waitcnt lgkmcnt(2)
	v_fma_f32 v0, -v62, v234, v0
	v_fma_f32 v4, -v63, v235, v4
	v_fma_f32 v20, -v64, v236, v20
	v_fma_f32 v66, -v65, v237, v66
	ds_read_b128 v[234:237], v21 offset:58400
	v_add_f32_e32 v0, v0, v4
	v_add_f32_e32 v4, v20, v66
	v_add_f32_e32 v66, v0, v4
	v_mul_f32_e32 v0, v241, v197
	v_mul_f32_e32 v1, v0, v245
	v_cndmask_b32_e64 v0, v0, v1, s[26:27]
	s_waitcnt lgkmcnt(2)
	v_fma_f32 v0, -v8, v248, v0
	v_fma_f32 v1, -v9, v249, 0
	v_fma_f32 v4, -v10, v250, 0
	v_fma_f32 v5, -v11, v251, 0
	ds_read_b128 v[248:251], v21 offset:58416
	s_waitcnt lgkmcnt(2)
	v_fma_f32 v0, -v12, v252, v0
	v_fma_f32 v1, -v13, v253, v1
	v_fma_f32 v4, -v14, v254, v4
	v_fma_f32 v5, -v15, v255, v5
	ds_read_b32 v68, v21 offset:58496
	ds_read_b128 v[252:255], v21 offset:58432
	s_waitcnt lgkmcnt(3)
	v_fma_f32 v0, -v41, v234, v0
	v_fma_f32 v1, -v43, v235, v1
	v_fma_f32 v4, -v44, v236, v4
	v_fma_f32 v5, -v45, v237, v5
	ds_read_b128 v[234:237], v21 offset:58448
	s_waitcnt lgkmcnt(3)
	v_fma_f32 v0, -v46, v248, v0
	v_fma_f32 v1, -v47, v249, v1
	v_fma_f32 v4, -v48, v250, v4
	v_fma_f32 v5, -v49, v251, v5
	ds_read_b128 v[248:251], v21 offset:58464
	s_waitcnt lgkmcnt(2)
	v_fma_f32 v0, -v50, v252, v0
	v_fma_f32 v1, -v51, v253, v1
	v_fma_f32 v4, -v52, v254, v4
	v_fma_f32 v5, -v53, v255, v5
	ds_read_b128 v[252:255], v21 offset:58480
	s_waitcnt lgkmcnt(2)
	v_fma_f32 v0, -v54, v234, v0
	v_fma_f32 v1, -v55, v235, v1
	v_fma_f32 v4, -v56, v236, v4
	v_fma_f32 v5, -v57, v237, v5
	ds_read_b128 v[234:237], v21 offset:58624
	s_waitcnt lgkmcnt(2)
	v_fma_f32 v0, -v58, v248, v0
	v_fma_f32 v1, -v59, v249, v1
	v_fma_f32 v4, -v60, v250, v4
	v_fma_f32 v5, -v61, v251, v5
	ds_read_b128 v[248:251], v21 offset:58640
	s_waitcnt lgkmcnt(2)
	v_fma_f32 v20, -v62, v252, v0
	v_fma_f32 v67, -v63, v253, v1
	ds_read2_b32 v[0:1], v198 offset0:162 offset1:227
	v_fma_f32 v4, -v64, v254, v4
	v_fma_f32 v5, -v65, v255, v5
	ds_read_b128 v[252:255], v21 offset:58656
	v_add_f32_e32 v4, v4, v5
	s_waitcnt lgkmcnt(1)
	v_mul_f32_e32 v0, v242, v0
	v_fma_f32 v20, -v66, v68, v20
	v_mul_f32_e32 v2, v0, v246
	v_add_f32_e32 v20, v67, v20
	v_cndmask_b32_e64 v0, v0, v2, s[26:27]
	v_add_f32_e32 v67, v4, v20
	v_fma_f32 v0, -v8, v234, v0
	v_fma_f32 v2, -v9, v235, 0
	v_fma_f32 v4, -v10, v236, 0
	v_fma_f32 v5, -v11, v237, 0
	ds_read_b128 v[234:237], v21 offset:58672
	v_fma_f32 v0, -v12, v248, v0
	v_fma_f32 v2, -v13, v249, v2
	v_fma_f32 v4, -v14, v250, v4
	v_fma_f32 v5, -v15, v251, v5
	ds_read_b128 v[248:251], v21 offset:58688
	s_waitcnt lgkmcnt(2)
	v_fma_f32 v0, -v41, v252, v0
	v_fma_f32 v2, -v43, v253, v2
	v_fma_f32 v4, -v44, v254, v4
	v_fma_f32 v5, -v45, v255, v5
	ds_read_b128 v[252:255], v21 offset:58704
	s_waitcnt lgkmcnt(2)
	v_fma_f32 v0, -v46, v234, v0
	v_fma_f32 v2, -v47, v235, v2
	v_fma_f32 v4, -v48, v236, v4
	v_fma_f32 v5, -v49, v237, v5
	ds_read_b128 v[234:237], v21 offset:58720
	s_waitcnt lgkmcnt(2)
	v_fma_f32 v0, -v50, v248, v0
	v_fma_f32 v2, -v51, v249, v2
	v_fma_f32 v4, -v52, v250, v4
	v_fma_f32 v5, -v53, v251, v5
	ds_read_b128 v[248:251], v21 offset:58736
	s_waitcnt lgkmcnt(2)
	v_fma_f32 v0, -v54, v252, v0
	v_fma_f32 v2, -v55, v253, v2
	v_fma_f32 v4, -v56, v254, v4
	v_fma_f32 v5, -v57, v255, v5
	ds_read_b128 v[252:255], v21 offset:58880
	s_waitcnt lgkmcnt(2)
	v_fma_f32 v6, -v60, v236, v4
	v_fma_f32 v20, -v61, v237, v5
	ds_read_b64 v[4:5], v21 offset:58752
	v_fma_f32 v0, -v58, v234, v0
	v_fma_f32 v2, -v59, v235, v2
	ds_read_b128 v[234:237], v21 offset:58896
	s_waitcnt lgkmcnt(3)
	v_fma_f32 v0, -v62, v248, v0
	v_fma_f32 v2, -v63, v249, v2
	v_fma_f32 v6, -v64, v250, v6
	v_fma_f32 v20, -v65, v251, v20
	ds_read_b128 v[248:251], v21 offset:58912
	s_waitcnt lgkmcnt(2)
	v_fma_f32 v0, -v66, v4, v0
	v_fma_f32 v2, -v67, v5, v2
	v_add_f32_e32 v0, v0, v2
	v_add_f32_e32 v2, v6, v20
	v_add_f32_e32 v68, v2, v0
	v_mul_f32_e32 v0, v243, v1
	ds_read_b128 v[240:243], v21 offset:58928
	v_mul_f32_e32 v1, v0, v247
	ds_read_b128 v[244:247], v21 offset:58944
	v_cndmask_b32_e64 v4, v0, v1, s[26:27]
	v_fma_f32 v4, -v8, v252, v4
	v_fma_f32 v20, -v9, v253, 0
	v_fma_f32 v69, -v10, v254, 0
	v_fma_f32 v184, -v11, v255, 0
	ds_read_b128 v[252:255], v21 offset:58960
	s_waitcnt lgkmcnt(4)
	v_fma_f32 v185, -v12, v234, v4
	v_fma_f32 v20, -v13, v235, v20
	v_fma_f32 v69, -v14, v236, v69
	v_fma_f32 v184, -v15, v237, v184
	ds_read_b128 v[234:237], v21 offset:58976
	s_waitcnt lgkmcnt(4)
	v_fma_f32 v4, -v41, v248, v185
	v_fma_f32 v20, -v43, v249, v20
	v_fma_f32 v69, -v44, v250, v69
	v_fma_f32 v184, -v45, v251, v184
	ds_read_b128 v[248:251], v21 offset:58992
	s_waitcnt lgkmcnt(4)
	v_fma_f32 v185, -v46, v240, v4
	v_fma_f32 v20, -v47, v241, v20
	v_fma_f32 v69, -v48, v242, v69
	v_fma_f32 v184, -v49, v243, v184
	ds_read_b128 v[240:243], v113
	s_waitcnt lgkmcnt(4)
	v_fma_f32 v4, -v50, v244, v185
	v_fma_f32 v20, -v51, v245, v20
	ds_read_b128 v[196:199], v21 offset:59184
	v_fma_f32 v69, -v52, v246, v69
	v_fma_f32 v184, -v53, v247, v184
	ds_read_b128 v[244:247], v114
	s_waitcnt lgkmcnt(5)
	v_fma_f32 v185, -v54, v252, v4
	ds_read_b96 v[4:6], v21 offset:59008
	v_fma_f32 v20, -v55, v253, v20
	v_fma_f32 v69, -v56, v254, v69
	v_fma_f32 v184, -v57, v255, v184
	ds_read_b128 v[252:255], v21 offset:59136
	s_waitcnt lgkmcnt(6)
	v_fma_f32 v185, -v58, v234, v185
	v_fma_f32 v20, -v59, v235, v20
	v_fma_f32 v69, -v60, v236, v69
	v_fma_f32 v7, -v61, v237, v184
	ds_read_b128 v[234:237], v21 offset:59152
	s_waitcnt lgkmcnt(6)
	v_fma_f32 v0, -v62, v248, v185
	v_fma_f32 v1, -v63, v249, v20
	v_fma_f32 v2, -v64, v250, v69
	v_add_u32_e32 v202, 0x2400, v88
	ds_read2_b32 v[200:201], v202 offset0:36 offset1:101
	v_fma_f32 v20, -v65, v251, v7
	ds_read_b128 v[248:251], v21 offset:59168
	s_waitcnt lgkmcnt(4)
	v_fma_f32 v69, -v66, v4, v0
	v_fma_f32 v184, -v67, v5, v1
	v_fma_f32 v185, -v68, v6, v2
	v_add_f32_e32 v69, v69, v184
	v_add_f32_e32 v20, v20, v185
	s_waitcnt lgkmcnt(1)
	v_mul_f32_e32 v0, v200, v240
	v_mul_f32_e32 v4, v0, v244
	v_cndmask_b32_e64 v0, v0, v4, s[26:27]
	v_fma_f32 v0, -v8, v252, v0
	v_fma_f32 v184, -v11, v255, 0
	v_fma_f32 v184, -v15, v237, v184
	v_add_f32_e32 v69, v69, v20
	v_fma_f32 v4, -v9, v253, 0
	v_fma_f32 v20, -v10, v254, 0
	ds_read_b128 v[252:255], v21 offset:59200
	v_fma_f32 v0, -v12, v234, v0
	s_waitcnt lgkmcnt(1)
	v_fma_f32 v188, -v45, v251, v184
	v_fma_f32 v4, -v13, v235, v4
	v_fma_f32 v20, -v14, v236, v20
	ds_read_b128 v[234:237], v21 offset:59216
	v_fma_f32 v0, -v41, v248, v0
	v_fma_f32 v4, -v43, v249, v4
	v_fma_f32 v20, -v44, v250, v20
	ds_read_b128 v[248:251], v21 offset:59232
	v_fma_f32 v0, -v46, v196, v0
	v_fma_f32 v4, -v47, v197, v4
	v_fma_f32 v20, -v48, v198, v20
	v_fma_f32 v192, -v49, v199, v188
	s_waitcnt lgkmcnt(2)
	v_fma_f32 v0, -v50, v252, v0
	v_fma_f32 v4, -v51, v253, v4
	v_fma_f32 v20, -v52, v254, v20
	v_fma_f32 v192, -v53, v255, v192
	ds_read_b128 v[252:255], v21 offset:59248
	s_waitcnt lgkmcnt(2)
	v_fma_f32 v0, -v54, v234, v0
	v_fma_f32 v4, -v55, v235, v4
	v_fma_f32 v20, -v56, v236, v20
	v_fma_f32 v192, -v57, v237, v192
	ds_read_b128 v[234:237], v21 offset:59264
	s_waitcnt lgkmcnt(2)
	v_fma_f32 v0, -v58, v248, v0
	v_fma_f32 v4, -v59, v249, v4
	v_fma_f32 v20, -v60, v250, v20
	v_fma_f32 v192, -v61, v251, v192
	ds_read_b128 v[248:251], v21 offset:59392
	s_waitcnt lgkmcnt(2)
	v_fma_f32 v0, -v62, v252, v0
	v_fma_f32 v4, -v63, v253, v4
	v_fma_f32 v20, -v64, v254, v20
	v_fma_f32 v192, -v65, v255, v192
	ds_read_b128 v[252:255], v21 offset:59408
	s_waitcnt lgkmcnt(2)
	v_fma_f32 v0, -v66, v234, v0
	v_fma_f32 v4, -v67, v235, v4
	v_fma_f32 v20, -v68, v236, v20
	v_fma_f32 v184, -v69, v237, v192
	ds_read_b128 v[234:237], v21 offset:59424
	v_add_f32_e32 v0, v0, v4
	v_add_f32_e32 v4, v20, v184
	v_add_f32_e32 v184, v0, v4
	v_mul_f32_e32 v0, v241, v201
	v_mul_f32_e32 v1, v0, v245
	v_cndmask_b32_e64 v0, v0, v1, s[26:27]
	s_waitcnt lgkmcnt(2)
	v_fma_f32 v0, -v8, v248, v0
	v_fma_f32 v1, -v9, v249, 0
	v_fma_f32 v4, -v10, v250, 0
	v_fma_f32 v5, -v11, v251, 0
	ds_read_b128 v[248:251], v21 offset:59440
	s_waitcnt lgkmcnt(2)
	v_fma_f32 v0, -v12, v252, v0
	v_fma_f32 v1, -v13, v253, v1
	v_fma_f32 v4, -v14, v254, v4
	ds_read_b32 v190, v21 offset:59536
	v_fma_f32 v5, -v15, v255, v5
	ds_read_b128 v[252:255], v21 offset:59456
	s_waitcnt lgkmcnt(3)
	v_fma_f32 v0, -v41, v234, v0
	v_fma_f32 v1, -v43, v235, v1
	v_fma_f32 v4, -v44, v236, v4
	v_fma_f32 v5, -v45, v237, v5
	ds_read_b128 v[234:237], v21 offset:59472
	s_waitcnt lgkmcnt(3)
	v_fma_f32 v0, -v46, v248, v0
	v_fma_f32 v1, -v47, v249, v1
	v_fma_f32 v4, -v48, v250, v4
	v_fma_f32 v5, -v49, v251, v5
	ds_read_b128 v[248:251], v21 offset:59488
	s_waitcnt lgkmcnt(2)
	v_fma_f32 v0, -v50, v252, v0
	v_fma_f32 v1, -v51, v253, v1
	v_fma_f32 v4, -v52, v254, v4
	v_fma_f32 v5, -v53, v255, v5
	ds_read_b128 v[252:255], v21 offset:59504
	s_waitcnt lgkmcnt(2)
	v_fma_f32 v0, -v54, v234, v0
	v_fma_f32 v1, -v55, v235, v1
	v_fma_f32 v4, -v56, v236, v4
	v_fma_f32 v5, -v57, v237, v5
	ds_read_b128 v[234:237], v21 offset:59520
	s_waitcnt lgkmcnt(2)
	v_fma_f32 v0, -v58, v248, v0
	v_fma_f32 v1, -v59, v249, v1
	v_fma_f32 v4, -v60, v250, v4
	v_fma_f32 v5, -v61, v251, v5
	ds_read_b128 v[248:251], v21 offset:59648
	s_waitcnt lgkmcnt(2)
	v_fma_f32 v0, -v62, v252, v0
	v_fma_f32 v1, -v63, v253, v1
	v_fma_f32 v4, -v64, v254, v4
	v_fma_f32 v5, -v65, v255, v5
	ds_read_b128 v[252:255], v21 offset:59664
	s_waitcnt lgkmcnt(2)
	v_fma_f32 v20, -v66, v234, v0
	v_fma_f32 v185, -v67, v235, v1
	ds_read2_b32 v[0:1], v202 offset0:166 offset1:231
	v_fma_f32 v4, -v68, v236, v4
	v_fma_f32 v5, -v69, v237, v5
	ds_read_b128 v[234:237], v21 offset:59680
	v_fma_f32 v20, -v184, v190, v20
	v_add_f32_e32 v20, v185, v20
	s_waitcnt lgkmcnt(1)
	v_mul_f32_e32 v0, v242, v0
	v_mul_f32_e32 v2, v0, v246
	v_add_f32_e32 v4, v4, v5
	v_cndmask_b32_e64 v0, v0, v2, s[26:27]
	v_add_f32_e32 v185, v4, v20
	v_fma_f32 v0, -v8, v248, v0
	v_fma_f32 v2, -v9, v249, 0
	v_fma_f32 v4, -v10, v250, 0
	v_fma_f32 v5, -v11, v251, 0
	ds_read_b128 v[248:251], v21 offset:59696
	v_fma_f32 v0, -v12, v252, v0
	v_fma_f32 v2, -v13, v253, v2
	v_fma_f32 v4, -v14, v254, v4
	v_fma_f32 v5, -v15, v255, v5
	ds_read_b128 v[252:255], v21 offset:59712
	s_waitcnt lgkmcnt(2)
	v_fma_f32 v0, -v41, v234, v0
	v_fma_f32 v2, -v43, v235, v2
	v_fma_f32 v4, -v44, v236, v4
	v_fma_f32 v5, -v45, v237, v5
	ds_read_b128 v[234:237], v21 offset:59728
	s_waitcnt lgkmcnt(2)
	v_fma_f32 v0, -v46, v248, v0
	v_fma_f32 v2, -v47, v249, v2
	v_fma_f32 v4, -v48, v250, v4
	v_fma_f32 v5, -v49, v251, v5
	ds_read_b128 v[248:251], v21 offset:59744
	s_waitcnt lgkmcnt(2)
	v_fma_f32 v0, -v50, v252, v0
	v_fma_f32 v2, -v51, v253, v2
	v_fma_f32 v4, -v52, v254, v4
	v_fma_f32 v5, -v53, v255, v5
	ds_read_b128 v[252:255], v21 offset:59760
	s_waitcnt lgkmcnt(2)
	v_fma_f32 v0, -v54, v234, v0
	v_fma_f32 v2, -v55, v235, v2
	v_fma_f32 v4, -v56, v236, v4
	v_fma_f32 v5, -v57, v237, v5
	ds_read_b128 v[234:237], v21 offset:59776
	s_waitcnt lgkmcnt(2)
	v_fma_f32 v0, -v58, v248, v0
	v_fma_f32 v2, -v59, v249, v2
	v_fma_f32 v4, -v60, v250, v4
	v_fma_f32 v5, -v61, v251, v5
	ds_read_b128 v[248:251], v21 offset:59904
	s_waitcnt lgkmcnt(2)
	v_fma_f32 v6, -v64, v254, v4
	v_fma_f32 v20, -v65, v255, v5
	ds_read_b64 v[4:5], v21 offset:59792
	v_fma_f32 v0, -v62, v252, v0
	v_fma_f32 v2, -v63, v253, v2
	ds_read_b128 v[252:255], v21 offset:59920
	s_waitcnt lgkmcnt(3)
	v_fma_f32 v0, -v66, v234, v0
	v_fma_f32 v2, -v67, v235, v2
	v_fma_f32 v6, -v68, v236, v6
	v_fma_f32 v20, -v69, v237, v20
	ds_read_b128 v[234:237], v21 offset:59936
	s_waitcnt lgkmcnt(2)
	v_fma_f32 v0, -v184, v4, v0
	v_fma_f32 v2, -v185, v5, v2
	v_add_f32_e32 v0, v0, v2
	v_add_f32_e32 v2, v6, v20
	v_add_f32_e32 v186, v2, v0
	v_mul_f32_e32 v0, v243, v1
	ds_read_b128 v[240:243], v21 offset:59952
	v_mul_f32_e32 v1, v0, v247
	ds_read_b128 v[244:247], v21 offset:59968
	v_cndmask_b32_e64 v0, v0, v1, s[26:27]
	v_fma_f32 v20, -v8, v248, v0
	v_fma_f32 v187, -v9, v249, 0
	v_fma_f32 v188, -v10, v250, 0
	v_fma_f32 v189, -v11, v251, 0
	ds_read_b128 v[248:251], v21 offset:59984
	s_waitcnt lgkmcnt(4)
	v_fma_f32 v0, -v12, v252, v20
	v_fma_f32 v20, -v13, v253, v187
	v_fma_f32 v187, -v14, v254, v188
	v_fma_f32 v188, -v15, v255, v189
	ds_read_b128 v[252:255], v21 offset:60000
	s_waitcnt lgkmcnt(4)
	v_fma_f32 v189, -v41, v234, v0
	v_fma_f32 v20, -v43, v235, v20
	v_fma_f32 v187, -v44, v236, v187
	v_fma_f32 v188, -v45, v237, v188
	ds_read_b128 v[234:237], v21 offset:60016
	s_waitcnt lgkmcnt(4)
	v_fma_f32 v0, -v46, v240, v189
	v_fma_f32 v20, -v47, v241, v20
	v_fma_f32 v187, -v48, v242, v187
	v_fma_f32 v188, -v49, v243, v188
	ds_read_b128 v[240:243], v21 offset:60032
	s_waitcnt lgkmcnt(4)
	v_fma_f32 v189, -v50, v244, v0
	v_fma_f32 v20, -v51, v245, v20
	v_fma_f32 v187, -v52, v246, v187
	v_fma_f32 v188, -v53, v247, v188
	ds_read_b128 v[244:247], v115
	s_waitcnt lgkmcnt(4)
	v_fma_f32 v0, -v54, v248, v189
	v_fma_f32 v20, -v55, v249, v20
	ds_read_b128 v[200:203], v21 offset:60208
	v_fma_f32 v187, -v56, v250, v187
	v_fma_f32 v188, -v57, v251, v188
	ds_read_b128 v[248:251], v116
	s_waitcnt lgkmcnt(5)
	v_fma_f32 v189, -v58, v252, v0
	ds_read_b96 v[0:2], v21 offset:60048
	v_fma_f32 v20, -v59, v253, v20
	v_fma_f32 v187, -v60, v254, v187
	v_fma_f32 v188, -v61, v255, v188
	ds_read_b128 v[252:255], v21 offset:60160
	s_waitcnt lgkmcnt(6)
	v_fma_f32 v189, -v62, v234, v189
	v_fma_f32 v20, -v63, v235, v20
	v_fma_f32 v187, -v64, v236, v187
	v_fma_f32 v3, -v65, v237, v188
	ds_read_b128 v[234:237], v21 offset:60176
	s_waitcnt lgkmcnt(6)
	v_fma_f32 v4, -v66, v240, v189
	v_fma_f32 v5, -v67, v241, v20
	v_fma_f32 v6, -v68, v242, v187
	v_add_u32_e32 v206, 0x2800, v88
	ds_read2_b32 v[204:205], v206 offset0:40 offset1:105
	v_fma_f32 v20, -v69, v243, v3
	ds_read_b128 v[240:243], v21 offset:60192
	s_waitcnt lgkmcnt(4)
	v_fma_f32 v187, -v184, v0, v4
	v_fma_f32 v188, -v185, v1, v5
	v_fma_f32 v189, -v186, v2, v6
	v_add_f32_e32 v187, v187, v188
	v_add_f32_e32 v20, v20, v189
	s_waitcnt lgkmcnt(1)
	v_mul_f32_e32 v0, v204, v244
	v_mul_f32_e32 v4, v0, v248
	v_cndmask_b32_e64 v0, v0, v4, s[26:27]
	v_fma_f32 v0, -v8, v252, v0
	v_fma_f32 v188, -v11, v255, 0
	v_fma_f32 v188, -v15, v237, v188
	v_add_f32_e32 v187, v187, v20
	v_fma_f32 v4, -v9, v253, 0
	v_fma_f32 v20, -v10, v254, 0
	ds_read_b128 v[252:255], v21 offset:60224
	v_fma_f32 v0, -v12, v234, v0
	s_waitcnt lgkmcnt(1)
	v_fma_f32 v192, -v45, v243, v188
	v_fma_f32 v4, -v13, v235, v4
	v_fma_f32 v20, -v14, v236, v20
	ds_read_b128 v[234:237], v21 offset:60240
	v_fma_f32 v0, -v41, v240, v0
	v_fma_f32 v196, -v49, v203, v192
	v_fma_f32 v4, -v43, v241, v4
	v_fma_f32 v20, -v44, v242, v20
	ds_read_b128 v[240:243], v21 offset:60256
	v_fma_f32 v0, -v46, v200, v0
	v_fma_f32 v4, -v47, v201, v4
	v_fma_f32 v20, -v48, v202, v20
	s_waitcnt lgkmcnt(2)
	v_fma_f32 v0, -v50, v252, v0
	v_fma_f32 v4, -v51, v253, v4
	v_fma_f32 v20, -v52, v254, v20
	v_fma_f32 v196, -v53, v255, v196
	ds_read_b128 v[252:255], v21 offset:60272
	s_waitcnt lgkmcnt(2)
	v_fma_f32 v0, -v54, v234, v0
	v_fma_f32 v4, -v55, v235, v4
	v_fma_f32 v20, -v56, v236, v20
	v_fma_f32 v196, -v57, v237, v196
	ds_read_b128 v[234:237], v21 offset:60288
	s_waitcnt lgkmcnt(2)
	v_fma_f32 v0, -v58, v240, v0
	v_fma_f32 v4, -v59, v241, v4
	v_fma_f32 v20, -v60, v242, v20
	v_fma_f32 v196, -v61, v243, v196
	ds_read_b128 v[240:243], v21 offset:60304
	s_waitcnt lgkmcnt(2)
	v_fma_f32 v0, -v62, v252, v0
	v_fma_f32 v4, -v63, v253, v4
	v_fma_f32 v20, -v64, v254, v20
	v_fma_f32 v196, -v65, v255, v196
	ds_read_b128 v[252:255], v21 offset:60416
	s_waitcnt lgkmcnt(2)
	v_fma_f32 v0, -v66, v234, v0
	v_fma_f32 v4, -v67, v235, v4
	v_fma_f32 v20, -v68, v236, v20
	v_fma_f32 v188, -v69, v237, v196
	ds_read_b128 v[234:237], v21 offset:60432
	s_waitcnt lgkmcnt(2)
	v_fma_f32 v0, -v184, v240, v0
	v_fma_f32 v4, -v185, v241, v4
	v_fma_f32 v20, -v186, v242, v20
	v_fma_f32 v188, -v187, v243, v188
	ds_read_b128 v[240:243], v21 offset:60448
	v_add_f32_e32 v0, v0, v4
	v_add_f32_e32 v4, v20, v188
	v_add_f32_e32 v188, v0, v4
	v_mul_f32_e32 v0, v245, v205
	v_mul_f32_e32 v1, v0, v249
	v_cndmask_b32_e64 v0, v0, v1, s[26:27]
	s_waitcnt lgkmcnt(2)
	v_fma_f32 v0, -v8, v252, v0
	v_fma_f32 v1, -v9, v253, 0
	v_fma_f32 v4, -v10, v254, 0
	v_fma_f32 v5, -v11, v255, 0
	ds_read_b128 v[252:255], v21 offset:60464
	s_waitcnt lgkmcnt(2)
	v_fma_f32 v0, -v12, v234, v0
	v_fma_f32 v1, -v13, v235, v1
	v_fma_f32 v4, -v14, v236, v4
	v_fma_f32 v5, -v15, v237, v5
	ds_read_b128 v[234:237], v21 offset:60480
	s_waitcnt lgkmcnt(2)
	v_fma_f32 v0, -v41, v240, v0
	v_fma_f32 v1, -v43, v241, v1
	v_fma_f32 v4, -v44, v242, v4
	v_fma_f32 v5, -v45, v243, v5
	ds_read_b128 v[240:243], v21 offset:60496
	s_waitcnt lgkmcnt(2)
	v_fma_f32 v0, -v46, v252, v0
	v_fma_f32 v1, -v47, v253, v1
	v_fma_f32 v4, -v48, v254, v4
	v_fma_f32 v5, -v49, v255, v5
	ds_read_b32 v194, v21 offset:60576
	ds_read_b128 v[252:255], v21 offset:60512
	s_waitcnt lgkmcnt(3)
	v_fma_f32 v0, -v50, v234, v0
	v_fma_f32 v1, -v51, v235, v1
	v_fma_f32 v4, -v52, v236, v4
	v_fma_f32 v5, -v53, v237, v5
	ds_read_b128 v[234:237], v21 offset:60528
	s_waitcnt lgkmcnt(3)
	v_fma_f32 v0, -v54, v240, v0
	v_fma_f32 v1, -v55, v241, v1
	v_fma_f32 v4, -v56, v242, v4
	v_fma_f32 v5, -v57, v243, v5
	ds_read_b128 v[240:243], v21 offset:60544
	s_waitcnt lgkmcnt(2)
	v_fma_f32 v0, -v58, v252, v0
	v_fma_f32 v1, -v59, v253, v1
	v_fma_f32 v4, -v60, v254, v4
	v_fma_f32 v5, -v61, v255, v5
	ds_read_b128 v[252:255], v21 offset:60560
	s_waitcnt lgkmcnt(2)
	v_fma_f32 v0, -v62, v234, v0
	v_fma_f32 v1, -v63, v235, v1
	v_fma_f32 v4, -v64, v236, v4
	v_fma_f32 v5, -v65, v237, v5
	ds_read_b128 v[234:237], v21 offset:60672
	s_waitcnt lgkmcnt(2)
	v_fma_f32 v0, -v66, v240, v0
	v_fma_f32 v1, -v67, v241, v1
	v_fma_f32 v4, -v68, v242, v4
	v_fma_f32 v5, -v69, v243, v5
	ds_read_b128 v[240:243], v21 offset:60688
	s_waitcnt lgkmcnt(2)
	v_fma_f32 v20, -v184, v252, v0
	v_fma_f32 v189, -v185, v253, v1
	ds_read2_b32 v[0:1], v206 offset0:170 offset1:235
	v_fma_f32 v4, -v186, v254, v4
	v_fma_f32 v5, -v187, v255, v5
	ds_read_b128 v[252:255], v21 offset:60704
	v_add_f32_e32 v4, v4, v5
	s_waitcnt lgkmcnt(1)
	v_mul_f32_e32 v0, v246, v0
	v_fma_f32 v20, -v188, v194, v20
	v_mul_f32_e32 v2, v0, v250
	v_add_f32_e32 v20, v189, v20
	v_cndmask_b32_e64 v0, v0, v2, s[26:27]
	v_add_f32_e32 v189, v4, v20
	v_fma_f32 v0, -v8, v234, v0
	v_fma_f32 v2, -v9, v235, 0
	v_fma_f32 v4, -v10, v236, 0
	v_fma_f32 v5, -v11, v237, 0
	ds_read_b128 v[234:237], v21 offset:60720
	v_fma_f32 v0, -v12, v240, v0
	v_fma_f32 v2, -v13, v241, v2
	v_fma_f32 v4, -v14, v242, v4
	v_fma_f32 v5, -v15, v243, v5
	ds_read_b128 v[240:243], v21 offset:60736
	s_waitcnt lgkmcnt(2)
	v_fma_f32 v0, -v41, v252, v0
	v_fma_f32 v2, -v43, v253, v2
	v_fma_f32 v4, -v44, v254, v4
	v_fma_f32 v5, -v45, v255, v5
	ds_read_b128 v[252:255], v21 offset:60752
	s_waitcnt lgkmcnt(2)
	v_fma_f32 v0, -v46, v234, v0
	v_fma_f32 v2, -v47, v235, v2
	v_fma_f32 v4, -v48, v236, v4
	v_fma_f32 v5, -v49, v237, v5
	ds_read_b128 v[234:237], v21 offset:60768
	s_waitcnt lgkmcnt(2)
	v_fma_f32 v0, -v50, v240, v0
	v_fma_f32 v2, -v51, v241, v2
	v_fma_f32 v4, -v52, v242, v4
	v_fma_f32 v5, -v53, v243, v5
	ds_read_b128 v[240:243], v21 offset:60784
	s_waitcnt lgkmcnt(2)
	v_fma_f32 v0, -v54, v252, v0
	v_fma_f32 v2, -v55, v253, v2
	v_fma_f32 v4, -v56, v254, v4
	v_fma_f32 v5, -v57, v255, v5
	ds_read_b128 v[252:255], v21 offset:60800
	s_waitcnt lgkmcnt(2)
	v_fma_f32 v0, -v58, v234, v0
	v_fma_f32 v2, -v59, v235, v2
	v_fma_f32 v4, -v60, v236, v4
	v_fma_f32 v5, -v61, v237, v5
	ds_read_b128 v[234:237], v21 offset:60816
	s_waitcnt lgkmcnt(2)
	v_fma_f32 v0, -v62, v240, v0
	v_fma_f32 v2, -v63, v241, v2
	v_fma_f32 v4, -v64, v242, v4
	v_fma_f32 v5, -v65, v243, v5
	ds_read_b128 v[240:243], v21 offset:60928
	s_waitcnt lgkmcnt(2)
	v_fma_f32 v6, -v68, v254, v4
	v_fma_f32 v20, -v69, v255, v5
	ds_read_b64 v[4:5], v21 offset:60832
	v_fma_f32 v0, -v66, v252, v0
	v_fma_f32 v2, -v67, v253, v2
	ds_read_b128 v[252:255], v21 offset:60944
	s_waitcnt lgkmcnt(3)
	v_fma_f32 v0, -v184, v234, v0
	v_fma_f32 v2, -v185, v235, v2
	v_fma_f32 v6, -v186, v236, v6
	v_fma_f32 v20, -v187, v237, v20
	ds_read_b128 v[234:237], v21 offset:60960
	s_waitcnt lgkmcnt(2)
	v_fma_f32 v0, -v188, v4, v0
	v_fma_f32 v2, -v189, v5, v2
	v_add_f32_e32 v0, v0, v2
	v_add_f32_e32 v2, v6, v20
	v_add_f32_e32 v190, v2, v0
	v_mul_f32_e32 v0, v247, v1
	ds_read_b128 v[244:247], v21 offset:60976
	v_mul_f32_e32 v1, v0, v251
	ds_read_b128 v[248:251], v21 offset:60992
	v_cndmask_b32_e64 v4, v0, v1, s[26:27]
	v_add_u32_e32 v216, 0x2c00, v88
	v_fma_f32 v4, -v8, v240, v4
	v_fma_f32 v20, -v9, v241, 0
	v_fma_f32 v191, -v10, v242, 0
	v_fma_f32 v192, -v11, v243, 0
	ds_read_b128 v[240:243], v21 offset:61008
	s_waitcnt lgkmcnt(4)
	v_fma_f32 v193, -v12, v252, v4
	v_fma_f32 v20, -v13, v253, v20
	v_fma_f32 v191, -v14, v254, v191
	v_fma_f32 v192, -v15, v255, v192
	ds_read_b128 v[252:255], v21 offset:61024
	s_waitcnt lgkmcnt(4)
	v_fma_f32 v4, -v41, v234, v193
	v_fma_f32 v20, -v43, v235, v20
	v_fma_f32 v191, -v44, v236, v191
	v_fma_f32 v192, -v45, v237, v192
	ds_read_b128 v[234:237], v21 offset:61040
	s_waitcnt lgkmcnt(4)
	v_fma_f32 v193, -v46, v244, v4
	v_fma_f32 v20, -v47, v245, v20
	v_fma_f32 v191, -v48, v246, v191
	v_fma_f32 v192, -v49, v247, v192
	ds_read_b128 v[244:247], v21 offset:61056
	s_waitcnt lgkmcnt(4)
	v_fma_f32 v4, -v50, v248, v193
	v_fma_f32 v20, -v51, v249, v20
	v_fma_f32 v191, -v52, v250, v191
	v_fma_f32 v192, -v53, v251, v192
	ds_read_b128 v[248:251], v21 offset:61072
	s_waitcnt lgkmcnt(4)
	v_fma_f32 v193, -v54, v240, v4
	ds_read2_b32 v[214:215], v216 offset0:44 offset1:109
	v_fma_f32 v20, -v55, v241, v20
	v_fma_f32 v191, -v56, v242, v191
	v_fma_f32 v192, -v57, v243, v192
	ds_read_b128 v[240:243], v117
	ds_read_b128 v[204:207], v21 offset:61232
	s_waitcnt lgkmcnt(6)
	v_fma_f32 v4, -v58, v252, v193
	v_fma_f32 v20, -v59, v253, v20
	v_fma_f32 v191, -v60, v254, v191
	v_fma_f32 v192, -v61, v255, v192
	ds_read_b128 v[252:255], v118
	s_waitcnt lgkmcnt(6)
	v_fma_f32 v193, -v62, v234, v4
	ds_read_b96 v[4:6], v21 offset:61088
	v_fma_f32 v20, -v63, v235, v20
	v_fma_f32 v191, -v64, v236, v191
	v_fma_f32 v192, -v65, v237, v192
	ds_read_b128 v[234:237], v21 offset:61184
	s_waitcnt lgkmcnt(7)
	v_fma_f32 v193, -v66, v244, v193
	v_fma_f32 v20, -v67, v245, v20
	v_fma_f32 v191, -v68, v246, v191
	v_fma_f32 v7, -v69, v247, v192
	ds_read_b128 v[244:247], v21 offset:61200
	s_waitcnt lgkmcnt(7)
	v_fma_f32 v0, -v184, v248, v193
	v_fma_f32 v1, -v185, v249, v20
	v_fma_f32 v2, -v186, v250, v191
	v_fma_f32 v20, -v187, v251, v7
	ds_read_b128 v[248:251], v21 offset:61216
	s_waitcnt lgkmcnt(3)
	v_fma_f32 v191, -v188, v4, v0
	v_fma_f32 v192, -v189, v5, v1
	v_fma_f32 v193, -v190, v6, v2
	v_add_f32_e32 v191, v191, v192
	v_add_f32_e32 v20, v20, v193
	v_mul_f32_e32 v0, v214, v240
	v_mul_f32_e32 v4, v0, v252
	v_cndmask_b32_e64 v0, v0, v4, s[26:27]
	s_waitcnt lgkmcnt(2)
	v_fma_f32 v0, -v8, v234, v0
	v_fma_f32 v192, -v11, v237, 0
	s_waitcnt lgkmcnt(1)
	v_fma_f32 v192, -v15, v247, v192
	v_add_f32_e32 v191, v191, v20
	v_fma_f32 v4, -v9, v235, 0
	v_fma_f32 v20, -v10, v236, 0
	ds_read_b128 v[234:237], v21 offset:61248
	v_fma_f32 v0, -v12, v244, v0
	s_waitcnt lgkmcnt(1)
	v_fma_f32 v196, -v45, v251, v192
	v_fma_f32 v4, -v13, v245, v4
	v_fma_f32 v20, -v14, v246, v20
	ds_read_b128 v[244:247], v21 offset:61264
	v_fma_f32 v0, -v41, v248, v0
	v_fma_f32 v4, -v43, v249, v4
	v_fma_f32 v20, -v44, v250, v20
	ds_read_b128 v[248:251], v21 offset:61280
	v_fma_f32 v0, -v46, v204, v0
	v_fma_f32 v4, -v47, v205, v4
	v_fma_f32 v20, -v48, v206, v20
	v_fma_f32 v200, -v49, v207, v196
	s_waitcnt lgkmcnt(2)
	v_fma_f32 v0, -v50, v234, v0
	v_fma_f32 v4, -v51, v235, v4
	v_fma_f32 v20, -v52, v236, v20
	v_fma_f32 v200, -v53, v237, v200
	ds_read_b128 v[234:237], v21 offset:61296
	s_waitcnt lgkmcnt(2)
	v_fma_f32 v0, -v54, v244, v0
	v_fma_f32 v4, -v55, v245, v4
	v_fma_f32 v20, -v56, v246, v20
	v_fma_f32 v200, -v57, v247, v200
	ds_read_b128 v[244:247], v21 offset:61312
	s_waitcnt lgkmcnt(2)
	v_fma_f32 v0, -v58, v248, v0
	v_fma_f32 v4, -v59, v249, v4
	v_fma_f32 v20, -v60, v250, v20
	v_fma_f32 v200, -v61, v251, v200
	ds_read_b128 v[248:251], v21 offset:61328
	s_waitcnt lgkmcnt(2)
	v_fma_f32 v0, -v62, v234, v0
	v_fma_f32 v4, -v63, v235, v4
	v_fma_f32 v20, -v64, v236, v20
	v_fma_f32 v200, -v65, v237, v200
	ds_read_b128 v[234:237], v21 offset:61344
	s_waitcnt lgkmcnt(2)
	v_fma_f32 v0, -v66, v244, v0
	v_fma_f32 v4, -v67, v245, v4
	v_fma_f32 v20, -v68, v246, v20
	v_fma_f32 v200, -v69, v247, v200
	ds_read_b128 v[244:247], v21 offset:61440
	s_waitcnt lgkmcnt(2)
	v_fma_f32 v0, -v184, v248, v0
	v_fma_f32 v4, -v185, v249, v4
	v_fma_f32 v20, -v186, v250, v20
	v_fma_f32 v200, -v187, v251, v200
	ds_read_b128 v[248:251], v21 offset:61456
	s_waitcnt lgkmcnt(2)
	v_fma_f32 v0, -v188, v234, v0
	v_fma_f32 v4, -v189, v235, v4
	v_fma_f32 v20, -v190, v236, v20
	v_fma_f32 v192, -v191, v237, v200
	ds_read_b128 v[234:237], v21 offset:61472
	v_add_f32_e32 v0, v0, v4
	v_add_f32_e32 v4, v20, v192
	v_add_f32_e32 v192, v0, v4
	v_mul_f32_e32 v0, v241, v215
	v_mul_f32_e32 v1, v0, v253
	v_cndmask_b32_e64 v0, v0, v1, s[26:27]
	s_waitcnt lgkmcnt(2)
	v_fma_f32 v0, -v8, v244, v0
	v_fma_f32 v1, -v9, v245, 0
	v_fma_f32 v4, -v10, v246, 0
	v_fma_f32 v5, -v11, v247, 0
	ds_read_b128 v[244:247], v21 offset:61488
	s_waitcnt lgkmcnt(2)
	v_fma_f32 v0, -v12, v248, v0
	v_fma_f32 v1, -v13, v249, v1
	v_fma_f32 v4, -v14, v250, v4
	v_fma_f32 v5, -v15, v251, v5
	ds_read_b128 v[248:251], v21 offset:61504
	s_waitcnt lgkmcnt(2)
	v_fma_f32 v0, -v41, v234, v0
	v_fma_f32 v1, -v43, v235, v1
	v_fma_f32 v4, -v44, v236, v4
	v_fma_f32 v5, -v45, v237, v5
	ds_read_b128 v[234:237], v21 offset:61520
	s_waitcnt lgkmcnt(2)
	v_fma_f32 v0, -v46, v244, v0
	v_fma_f32 v1, -v47, v245, v1
	v_fma_f32 v4, -v48, v246, v4
	ds_read_b32 v198, v21 offset:61616
	v_fma_f32 v5, -v49, v247, v5
	ds_read_b128 v[244:247], v21 offset:61536
	s_waitcnt lgkmcnt(3)
	v_fma_f32 v0, -v50, v248, v0
	v_fma_f32 v1, -v51, v249, v1
	v_fma_f32 v4, -v52, v250, v4
	v_fma_f32 v5, -v53, v251, v5
	ds_read_b128 v[248:251], v21 offset:61552
	s_waitcnt lgkmcnt(3)
	v_fma_f32 v0, -v54, v234, v0
	v_fma_f32 v1, -v55, v235, v1
	v_fma_f32 v4, -v56, v236, v4
	v_fma_f32 v5, -v57, v237, v5
	ds_read_b128 v[234:237], v21 offset:61568
	s_waitcnt lgkmcnt(2)
	v_fma_f32 v0, -v58, v244, v0
	v_fma_f32 v1, -v59, v245, v1
	v_fma_f32 v4, -v60, v246, v4
	v_fma_f32 v5, -v61, v247, v5
	ds_read_b128 v[244:247], v21 offset:61584
	s_waitcnt lgkmcnt(2)
	v_fma_f32 v0, -v62, v248, v0
	v_fma_f32 v1, -v63, v249, v1
	v_fma_f32 v4, -v64, v250, v4
	v_fma_f32 v5, -v65, v251, v5
	ds_read_b128 v[248:251], v21 offset:61600
	s_waitcnt lgkmcnt(2)
	v_fma_f32 v0, -v66, v234, v0
	v_fma_f32 v1, -v67, v235, v1
	v_fma_f32 v4, -v68, v236, v4
	v_fma_f32 v5, -v69, v237, v5
	ds_read_b128 v[234:237], v21 offset:61696
	s_waitcnt lgkmcnt(2)
	v_fma_f32 v0, -v184, v244, v0
	v_fma_f32 v1, -v185, v245, v1
	v_fma_f32 v4, -v186, v246, v4
	v_fma_f32 v5, -v187, v247, v5
	ds_read_b128 v[244:247], v21 offset:61712
	s_waitcnt lgkmcnt(2)
	v_fma_f32 v20, -v188, v248, v0
	v_fma_f32 v193, -v189, v249, v1
	ds_read2_b32 v[0:1], v216 offset0:174 offset1:239
	v_fma_f32 v4, -v190, v250, v4
	v_fma_f32 v5, -v191, v251, v5
	ds_read_b128 v[248:251], v21 offset:61728
	v_fma_f32 v20, -v192, v198, v20
	v_add_f32_e32 v20, v193, v20
	s_waitcnt lgkmcnt(1)
	v_mul_f32_e32 v0, v242, v0
	v_mul_f32_e32 v2, v0, v254
	v_add_f32_e32 v4, v4, v5
	v_cndmask_b32_e64 v0, v0, v2, s[26:27]
	v_add_f32_e32 v193, v4, v20
	v_fma_f32 v0, -v8, v234, v0
	v_fma_f32 v2, -v9, v235, 0
	v_fma_f32 v4, -v10, v236, 0
	v_fma_f32 v5, -v11, v237, 0
	ds_read_b128 v[234:237], v21 offset:61744
	v_fma_f32 v0, -v12, v244, v0
	v_fma_f32 v2, -v13, v245, v2
	v_fma_f32 v4, -v14, v246, v4
	v_fma_f32 v5, -v15, v247, v5
	ds_read_b128 v[244:247], v21 offset:61760
	s_waitcnt lgkmcnt(2)
	v_fma_f32 v0, -v41, v248, v0
	v_fma_f32 v2, -v43, v249, v2
	v_fma_f32 v4, -v44, v250, v4
	v_fma_f32 v5, -v45, v251, v5
	ds_read_b128 v[248:251], v21 offset:61776
	s_waitcnt lgkmcnt(2)
	v_fma_f32 v0, -v46, v234, v0
	v_fma_f32 v2, -v47, v235, v2
	v_fma_f32 v4, -v48, v236, v4
	v_fma_f32 v5, -v49, v237, v5
	ds_read_b128 v[234:237], v21 offset:61792
	s_waitcnt lgkmcnt(2)
	v_fma_f32 v0, -v50, v244, v0
	v_fma_f32 v2, -v51, v245, v2
	v_fma_f32 v4, -v52, v246, v4
	v_fma_f32 v5, -v53, v247, v5
	ds_read_b128 v[244:247], v21 offset:61808
	s_waitcnt lgkmcnt(2)
	v_fma_f32 v0, -v54, v248, v0
	v_fma_f32 v2, -v55, v249, v2
	v_fma_f32 v4, -v56, v250, v4
	v_fma_f32 v5, -v57, v251, v5
	ds_read_b128 v[248:251], v21 offset:61824
	s_waitcnt lgkmcnt(2)
	v_fma_f32 v0, -v58, v234, v0
	v_fma_f32 v2, -v59, v235, v2
	v_fma_f32 v4, -v60, v236, v4
	v_fma_f32 v5, -v61, v237, v5
	ds_read_b128 v[234:237], v21 offset:61840
	s_waitcnt lgkmcnt(2)
	v_fma_f32 v0, -v62, v244, v0
	v_fma_f32 v2, -v63, v245, v2
	v_fma_f32 v4, -v64, v246, v4
	v_fma_f32 v5, -v65, v247, v5
	ds_read_b128 v[244:247], v21 offset:61856
	s_waitcnt lgkmcnt(2)
	v_fma_f32 v0, -v66, v248, v0
	v_fma_f32 v2, -v67, v249, v2
	v_fma_f32 v4, -v68, v250, v4
	v_fma_f32 v5, -v69, v251, v5
	ds_read_b128 v[248:251], v21 offset:61952
	s_waitcnt lgkmcnt(2)
	v_fma_f32 v6, -v186, v236, v4
	v_fma_f32 v20, -v187, v237, v5
	ds_read_b64 v[4:5], v21 offset:61872
	v_fma_f32 v0, -v184, v234, v0
	v_fma_f32 v2, -v185, v235, v2
	ds_read_b128 v[234:237], v21 offset:61968
	s_waitcnt lgkmcnt(3)
	v_fma_f32 v0, -v188, v244, v0
	v_fma_f32 v2, -v189, v245, v2
	v_fma_f32 v6, -v190, v246, v6
	v_fma_f32 v20, -v191, v247, v20
	ds_read_b128 v[244:247], v21 offset:61984
	s_waitcnt lgkmcnt(2)
	v_fma_f32 v0, -v192, v4, v0
	v_fma_f32 v2, -v193, v5, v2
	v_add_f32_e32 v0, v0, v2
	v_add_f32_e32 v2, v6, v20
	v_add_f32_e32 v194, v2, v0
	v_mul_f32_e32 v0, v243, v1
	ds_read_b128 v[240:243], v21 offset:62000
	v_mul_f32_e32 v1, v0, v255
	ds_read_b128 v[252:255], v21 offset:62016
	v_cndmask_b32_e64 v0, v0, v1, s[26:27]
	v_fma_f32 v20, -v8, v248, v0
	v_fma_f32 v195, -v9, v249, 0
	v_fma_f32 v196, -v10, v250, 0
	v_fma_f32 v197, -v11, v251, 0
	ds_read_b128 v[248:251], v21 offset:62032
	s_waitcnt lgkmcnt(4)
	v_fma_f32 v0, -v12, v234, v20
	v_fma_f32 v20, -v13, v235, v195
	v_fma_f32 v195, -v14, v236, v196
	v_fma_f32 v196, -v15, v237, v197
	ds_read_b128 v[234:237], v21 offset:62048
	s_waitcnt lgkmcnt(4)
	v_fma_f32 v197, -v41, v244, v0
	v_fma_f32 v20, -v43, v245, v20
	v_fma_f32 v195, -v44, v246, v195
	v_fma_f32 v196, -v45, v247, v196
	ds_read_b128 v[244:247], v21 offset:62064
	s_waitcnt lgkmcnt(4)
	v_fma_f32 v0, -v46, v240, v197
	v_fma_f32 v20, -v47, v241, v20
	v_fma_f32 v195, -v48, v242, v195
	v_fma_f32 v196, -v49, v243, v196
	ds_read_b128 v[240:243], v21 offset:62080
	s_waitcnt lgkmcnt(4)
	v_fma_f32 v197, -v50, v252, v0
	v_fma_f32 v20, -v51, v253, v20
	v_fma_f32 v195, -v52, v254, v195
	v_fma_f32 v196, -v53, v255, v196
	ds_read_b128 v[252:255], v21 offset:62096
	s_waitcnt lgkmcnt(4)
	v_fma_f32 v0, -v54, v248, v197
	v_fma_f32 v20, -v55, v249, v20
	v_fma_f32 v195, -v56, v250, v195
	v_fma_f32 v196, -v57, v251, v196
	ds_read_b128 v[248:251], v21 offset:62112
	s_waitcnt lgkmcnt(4)
	v_fma_f32 v197, -v58, v234, v0
	v_fma_f32 v20, -v59, v235, v20
	v_fma_f32 v195, -v60, v236, v195
	v_fma_f32 v196, -v61, v237, v196
	ds_read_b128 v[234:237], v119
	s_waitcnt lgkmcnt(4)
	v_fma_f32 v0, -v62, v244, v197
	v_fma_f32 v20, -v63, v245, v20
	ds_read_b128 v[214:217], v21 offset:62256
	v_fma_f32 v195, -v64, v246, v195
	v_fma_f32 v196, -v65, v247, v196
	ds_read_b128 v[244:247], v120
	s_waitcnt lgkmcnt(5)
	v_fma_f32 v197, -v66, v240, v0
	ds_read_b96 v[0:2], v21 offset:62128
	v_fma_f32 v20, -v67, v241, v20
	v_fma_f32 v195, -v68, v242, v195
	v_fma_f32 v196, -v69, v243, v196
	ds_read_b128 v[240:243], v21 offset:62208
	s_waitcnt lgkmcnt(6)
	v_fma_f32 v197, -v184, v252, v197
	v_fma_f32 v20, -v185, v253, v20
	v_fma_f32 v195, -v186, v254, v195
	v_fma_f32 v3, -v187, v255, v196
	ds_read_b128 v[252:255], v21 offset:62224
	s_waitcnt lgkmcnt(6)
	v_fma_f32 v4, -v188, v248, v197
	v_fma_f32 v5, -v189, v249, v20
	v_fma_f32 v6, -v190, v250, v195
	v_add_u32_e32 v220, 0x3000, v88
	ds_read2_b32 v[218:219], v220 offset0:48 offset1:113
	v_fma_f32 v20, -v191, v251, v3
	ds_read_b128 v[248:251], v21 offset:62240
	s_waitcnt lgkmcnt(4)
	v_fma_f32 v195, -v192, v0, v4
	v_fma_f32 v196, -v193, v1, v5
	v_fma_f32 v197, -v194, v2, v6
	v_add_f32_e32 v195, v195, v196
	v_add_f32_e32 v20, v20, v197
	s_waitcnt lgkmcnt(1)
	v_mul_f32_e32 v0, v218, v234
	v_mul_f32_e32 v4, v0, v244
	v_cndmask_b32_e64 v0, v0, v4, s[26:27]
	v_fma_f32 v0, -v8, v240, v0
	v_fma_f32 v196, -v11, v243, 0
	v_fma_f32 v196, -v15, v255, v196
	v_add_f32_e32 v195, v195, v20
	v_fma_f32 v4, -v9, v241, 0
	v_fma_f32 v20, -v10, v242, 0
	ds_read_b128 v[240:243], v21 offset:62272
	v_fma_f32 v0, -v12, v252, v0
	s_waitcnt lgkmcnt(1)
	v_fma_f32 v200, -v45, v251, v196
	v_fma_f32 v4, -v13, v253, v4
	v_fma_f32 v20, -v14, v254, v20
	ds_read_b128 v[252:255], v21 offset:62288
	v_fma_f32 v0, -v41, v248, v0
	v_fma_f32 v204, -v49, v217, v200
	v_fma_f32 v4, -v43, v249, v4
	v_fma_f32 v20, -v44, v250, v20
	ds_read_b128 v[248:251], v21 offset:62304
	v_fma_f32 v0, -v46, v214, v0
	v_fma_f32 v4, -v47, v215, v4
	v_fma_f32 v20, -v48, v216, v20
	s_waitcnt lgkmcnt(2)
	v_fma_f32 v0, -v50, v240, v0
	v_fma_f32 v4, -v51, v241, v4
	v_fma_f32 v20, -v52, v242, v20
	v_fma_f32 v204, -v53, v243, v204
	ds_read_b128 v[240:243], v21 offset:62320
	s_waitcnt lgkmcnt(2)
	v_fma_f32 v0, -v54, v252, v0
	v_fma_f32 v4, -v55, v253, v4
	v_fma_f32 v20, -v56, v254, v20
	v_fma_f32 v204, -v57, v255, v204
	ds_read_b128 v[252:255], v21 offset:62336
	s_waitcnt lgkmcnt(2)
	v_fma_f32 v0, -v58, v248, v0
	v_fma_f32 v4, -v59, v249, v4
	v_fma_f32 v20, -v60, v250, v20
	v_fma_f32 v204, -v61, v251, v204
	ds_read_b128 v[248:251], v21 offset:62352
	s_waitcnt lgkmcnt(2)
	v_fma_f32 v0, -v62, v240, v0
	v_fma_f32 v4, -v63, v241, v4
	v_fma_f32 v20, -v64, v242, v20
	v_fma_f32 v204, -v65, v243, v204
	ds_read_b128 v[240:243], v21 offset:62368
	s_waitcnt lgkmcnt(2)
	v_fma_f32 v0, -v66, v252, v0
	v_fma_f32 v4, -v67, v253, v4
	v_fma_f32 v20, -v68, v254, v20
	v_fma_f32 v204, -v69, v255, v204
	ds_read_b128 v[252:255], v21 offset:62384
	s_waitcnt lgkmcnt(2)
	v_fma_f32 v0, -v184, v248, v0
	v_fma_f32 v4, -v185, v249, v4
	v_fma_f32 v20, -v186, v250, v20
	v_fma_f32 v204, -v187, v251, v204
	ds_read_b128 v[248:251], v21 offset:62464
	s_waitcnt lgkmcnt(2)
	v_fma_f32 v0, -v188, v240, v0
	v_fma_f32 v4, -v189, v241, v4
	v_fma_f32 v20, -v190, v242, v20
	v_fma_f32 v196, -v191, v243, v204
	ds_read_b128 v[240:243], v21 offset:62480
	s_waitcnt lgkmcnt(2)
	v_fma_f32 v0, -v192, v252, v0
	v_fma_f32 v4, -v193, v253, v4
	v_fma_f32 v20, -v194, v254, v20
	v_fma_f32 v196, -v195, v255, v196
	ds_read_b128 v[252:255], v21 offset:62496
	v_add_f32_e32 v0, v0, v4
	v_add_f32_e32 v4, v20, v196
	v_add_f32_e32 v196, v0, v4
	v_mul_f32_e32 v0, v235, v219
	v_mul_f32_e32 v1, v0, v245
	v_cndmask_b32_e64 v0, v0, v1, s[26:27]
	s_waitcnt lgkmcnt(2)
	v_fma_f32 v0, -v8, v248, v0
	v_fma_f32 v1, -v9, v249, 0
	v_fma_f32 v4, -v10, v250, 0
	v_fma_f32 v5, -v11, v251, 0
	ds_read_b128 v[248:251], v21 offset:62512
	s_waitcnt lgkmcnt(2)
	v_fma_f32 v0, -v12, v240, v0
	v_fma_f32 v1, -v13, v241, v1
	v_fma_f32 v4, -v14, v242, v4
	v_fma_f32 v5, -v15, v243, v5
	ds_read_b128 v[240:243], v21 offset:62528
	s_waitcnt lgkmcnt(2)
	v_fma_f32 v0, -v41, v252, v0
	v_fma_f32 v1, -v43, v253, v1
	v_fma_f32 v4, -v44, v254, v4
	v_fma_f32 v5, -v45, v255, v5
	ds_read_b128 v[252:255], v21 offset:62544
	s_waitcnt lgkmcnt(2)
	v_fma_f32 v0, -v46, v248, v0
	v_fma_f32 v1, -v47, v249, v1
	v_fma_f32 v4, -v48, v250, v4
	v_fma_f32 v5, -v49, v251, v5
	ds_read_b128 v[248:251], v21 offset:62560
	s_waitcnt lgkmcnt(2)
	v_fma_f32 v0, -v50, v240, v0
	v_fma_f32 v1, -v51, v241, v1
	v_fma_f32 v4, -v52, v242, v4
	v_fma_f32 v5, -v53, v243, v5
	ds_read_b128 v[240:243], v21 offset:62576
	s_waitcnt lgkmcnt(2)
	v_fma_f32 v0, -v54, v252, v0
	v_fma_f32 v1, -v55, v253, v1
	v_fma_f32 v4, -v56, v254, v4
	v_fma_f32 v5, -v57, v255, v5
	ds_read_b32 v202, v21 offset:62656
	ds_read_b128 v[252:255], v21 offset:62592
	s_waitcnt lgkmcnt(3)
	v_fma_f32 v0, -v58, v248, v0
	v_fma_f32 v1, -v59, v249, v1
	v_fma_f32 v4, -v60, v250, v4
	v_fma_f32 v5, -v61, v251, v5
	ds_read_b128 v[248:251], v21 offset:62608
	s_waitcnt lgkmcnt(3)
	v_fma_f32 v0, -v62, v240, v0
	v_fma_f32 v1, -v63, v241, v1
	v_fma_f32 v4, -v64, v242, v4
	v_fma_f32 v5, -v65, v243, v5
	ds_read_b128 v[240:243], v21 offset:62624
	s_waitcnt lgkmcnt(2)
	v_fma_f32 v0, -v66, v252, v0
	v_fma_f32 v1, -v67, v253, v1
	v_fma_f32 v4, -v68, v254, v4
	v_fma_f32 v5, -v69, v255, v5
	ds_read_b128 v[252:255], v21 offset:62640
	s_waitcnt lgkmcnt(2)
	v_fma_f32 v0, -v184, v248, v0
	v_fma_f32 v1, -v185, v249, v1
	v_fma_f32 v4, -v186, v250, v4
	v_fma_f32 v5, -v187, v251, v5
	ds_read_b128 v[248:251], v21 offset:62720
	s_waitcnt lgkmcnt(2)
	v_fma_f32 v0, -v188, v240, v0
	v_fma_f32 v1, -v189, v241, v1
	v_fma_f32 v4, -v190, v242, v4
	v_fma_f32 v5, -v191, v243, v5
	ds_read_b128 v[240:243], v21 offset:62736
	s_waitcnt lgkmcnt(2)
	v_fma_f32 v20, -v192, v252, v0
	v_fma_f32 v197, -v193, v253, v1
	ds_read2_b32 v[0:1], v220 offset0:178 offset1:243
	v_fma_f32 v4, -v194, v254, v4
	v_fma_f32 v5, -v195, v255, v5
	ds_read_b128 v[252:255], v21 offset:62752
	v_add_f32_e32 v4, v4, v5
	s_waitcnt lgkmcnt(1)
	v_mul_f32_e32 v0, v236, v0
	v_fma_f32 v20, -v196, v202, v20
	v_mul_f32_e32 v2, v0, v246
	v_add_f32_e32 v20, v197, v20
	v_cndmask_b32_e64 v0, v0, v2, s[26:27]
	v_add_f32_e32 v197, v4, v20
	v_fma_f32 v0, -v8, v248, v0
	v_fma_f32 v2, -v9, v249, 0
	v_fma_f32 v4, -v10, v250, 0
	v_fma_f32 v5, -v11, v251, 0
	ds_read_b128 v[248:251], v21 offset:62768
	v_fma_f32 v0, -v12, v240, v0
	v_fma_f32 v2, -v13, v241, v2
	v_fma_f32 v4, -v14, v242, v4
	v_fma_f32 v5, -v15, v243, v5
	ds_read_b128 v[240:243], v21 offset:62784
	s_waitcnt lgkmcnt(2)
	v_fma_f32 v0, -v41, v252, v0
	v_fma_f32 v2, -v43, v253, v2
	v_fma_f32 v4, -v44, v254, v4
	v_fma_f32 v5, -v45, v255, v5
	ds_read_b128 v[252:255], v21 offset:62800
	s_waitcnt lgkmcnt(2)
	v_fma_f32 v0, -v46, v248, v0
	v_fma_f32 v2, -v47, v249, v2
	v_fma_f32 v4, -v48, v250, v4
	v_fma_f32 v5, -v49, v251, v5
	ds_read_b128 v[248:251], v21 offset:62816
	s_waitcnt lgkmcnt(2)
	v_fma_f32 v0, -v50, v240, v0
	v_fma_f32 v2, -v51, v241, v2
	v_fma_f32 v4, -v52, v242, v4
	v_fma_f32 v5, -v53, v243, v5
	ds_read_b128 v[240:243], v21 offset:62832
	s_waitcnt lgkmcnt(2)
	v_fma_f32 v0, -v54, v252, v0
	v_fma_f32 v2, -v55, v253, v2
	v_fma_f32 v4, -v56, v254, v4
	v_fma_f32 v5, -v57, v255, v5
	ds_read_b128 v[252:255], v21 offset:62848
	s_waitcnt lgkmcnt(2)
	v_fma_f32 v0, -v58, v248, v0
	v_fma_f32 v2, -v59, v249, v2
	v_fma_f32 v4, -v60, v250, v4
	v_fma_f32 v5, -v61, v251, v5
	ds_read_b128 v[248:251], v21 offset:62864
	s_waitcnt lgkmcnt(2)
	v_fma_f32 v0, -v62, v240, v0
	v_fma_f32 v2, -v63, v241, v2
	v_fma_f32 v4, -v64, v242, v4
	v_fma_f32 v5, -v65, v243, v5
	ds_read_b128 v[240:243], v21 offset:62880
	s_waitcnt lgkmcnt(2)
	v_fma_f32 v0, -v66, v252, v0
	v_fma_f32 v2, -v67, v253, v2
	v_fma_f32 v4, -v68, v254, v4
	v_fma_f32 v5, -v69, v255, v5
	ds_read_b128 v[252:255], v21 offset:62896
	s_waitcnt lgkmcnt(2)
	v_fma_f32 v0, -v184, v248, v0
	v_fma_f32 v2, -v185, v249, v2
	v_fma_f32 v4, -v186, v250, v4
	v_fma_f32 v5, -v187, v251, v5
	ds_read_b128 v[248:251], v21 offset:62976
	s_waitcnt lgkmcnt(2)
	v_fma_f32 v6, -v190, v242, v4
	v_fma_f32 v20, -v191, v243, v5
	ds_read_b64 v[4:5], v21 offset:62912
	v_fma_f32 v0, -v188, v240, v0
	v_fma_f32 v2, -v189, v241, v2
	ds_read_b128 v[240:243], v21 offset:62992
	s_waitcnt lgkmcnt(3)
	v_fma_f32 v0, -v192, v252, v0
	v_fma_f32 v2, -v193, v253, v2
	v_fma_f32 v6, -v194, v254, v6
	v_fma_f32 v20, -v195, v255, v20
	ds_read_b128 v[252:255], v21 offset:63008
	s_waitcnt lgkmcnt(2)
	v_fma_f32 v0, -v196, v4, v0
	v_fma_f32 v2, -v197, v5, v2
	v_add_f32_e32 v0, v0, v2
	v_add_f32_e32 v2, v6, v20
	v_add_f32_e32 v198, v2, v0
	v_mul_f32_e32 v0, v237, v1
	ds_read_b128 v[234:237], v21 offset:63024
	v_mul_f32_e32 v1, v0, v247
	ds_read_b128 v[244:247], v21 offset:63040
	v_cndmask_b32_e64 v4, v0, v1, s[26:27]
	v_add_u32_e32 v224, 0x3400, v88
	v_fma_f32 v4, -v8, v248, v4
	v_fma_f32 v20, -v9, v249, 0
	v_fma_f32 v199, -v10, v250, 0
	v_fma_f32 v200, -v11, v251, 0
	ds_read_b128 v[248:251], v21 offset:63056
	s_waitcnt lgkmcnt(4)
	v_fma_f32 v201, -v12, v240, v4
	v_fma_f32 v20, -v13, v241, v20
	v_fma_f32 v199, -v14, v242, v199
	v_fma_f32 v200, -v15, v243, v200
	ds_read_b128 v[240:243], v21 offset:63072
	s_waitcnt lgkmcnt(4)
	v_fma_f32 v4, -v41, v252, v201
	v_fma_f32 v20, -v43, v253, v20
	v_fma_f32 v199, -v44, v254, v199
	v_fma_f32 v200, -v45, v255, v200
	ds_read_b128 v[252:255], v21 offset:63088
	s_waitcnt lgkmcnt(4)
	v_fma_f32 v201, -v46, v234, v4
	v_fma_f32 v20, -v47, v235, v20
	v_fma_f32 v199, -v48, v236, v199
	v_fma_f32 v200, -v49, v237, v200
	ds_read_b128 v[234:237], v21 offset:63104
	s_waitcnt lgkmcnt(4)
	v_fma_f32 v4, -v50, v244, v201
	v_fma_f32 v20, -v51, v245, v20
	v_fma_f32 v199, -v52, v246, v199
	v_fma_f32 v200, -v53, v247, v200
	ds_read_b128 v[244:247], v21 offset:63120
	s_waitcnt lgkmcnt(4)
	v_fma_f32 v201, -v54, v248, v4
	v_fma_f32 v20, -v55, v249, v20
	v_fma_f32 v199, -v56, v250, v199
	v_fma_f32 v200, -v57, v251, v200
	ds_read_b128 v[248:251], v21 offset:63136
	s_waitcnt lgkmcnt(4)
	v_fma_f32 v4, -v58, v240, v201
	v_fma_f32 v20, -v59, v241, v20
	v_fma_f32 v199, -v60, v242, v199
	v_fma_f32 v200, -v61, v243, v200
	ds_read_b128 v[240:243], v21 offset:63152
	s_waitcnt lgkmcnt(4)
	v_fma_f32 v201, -v62, v252, v4
	ds_read2_b32 v[222:223], v224 offset0:52 offset1:117
	v_fma_f32 v20, -v63, v253, v20
	v_fma_f32 v199, -v64, v254, v199
	v_fma_f32 v200, -v65, v255, v200
	ds_read_b128 v[252:255], v121
	ds_read_b128 v[218:221], v21 offset:63280
	s_waitcnt lgkmcnt(6)
	v_fma_f32 v4, -v66, v234, v201
	v_fma_f32 v20, -v67, v235, v20
	v_fma_f32 v199, -v68, v236, v199
	v_fma_f32 v200, -v69, v237, v200
	ds_read_b128 v[234:237], v122
	s_waitcnt lgkmcnt(6)
	v_fma_f32 v201, -v184, v244, v4
	ds_read_b96 v[4:6], v21 offset:63168
	v_fma_f32 v20, -v185, v245, v20
	v_fma_f32 v199, -v186, v246, v199
	v_fma_f32 v200, -v187, v247, v200
	ds_read_b128 v[244:247], v21 offset:63232
	s_waitcnt lgkmcnt(7)
	v_fma_f32 v201, -v188, v248, v201
	v_fma_f32 v20, -v189, v249, v20
	v_fma_f32 v199, -v190, v250, v199
	v_fma_f32 v7, -v191, v251, v200
	ds_read_b128 v[248:251], v21 offset:63248
	s_waitcnt lgkmcnt(7)
	v_fma_f32 v0, -v192, v240, v201
	v_fma_f32 v1, -v193, v241, v20
	v_fma_f32 v2, -v194, v242, v199
	v_fma_f32 v20, -v195, v243, v7
	ds_read_b128 v[240:243], v21 offset:63264
	s_waitcnt lgkmcnt(3)
	v_fma_f32 v199, -v196, v4, v0
	v_fma_f32 v200, -v197, v5, v1
	v_fma_f32 v201, -v198, v6, v2
	v_add_f32_e32 v199, v199, v200
	v_add_f32_e32 v20, v20, v201
	v_mul_f32_e32 v0, v222, v252
	v_mul_f32_e32 v4, v0, v234
	v_cndmask_b32_e64 v0, v0, v4, s[26:27]
	s_waitcnt lgkmcnt(2)
	v_fma_f32 v0, -v8, v244, v0
	v_fma_f32 v200, -v11, v247, 0
	s_waitcnt lgkmcnt(1)
	v_fma_f32 v200, -v15, v251, v200
	v_add_f32_e32 v199, v199, v20
	v_fma_f32 v4, -v9, v245, 0
	v_fma_f32 v20, -v10, v246, 0
	ds_read_b128 v[244:247], v21 offset:63296
	v_fma_f32 v0, -v12, v248, v0
	s_waitcnt lgkmcnt(1)
	v_fma_f32 v204, -v45, v243, v200
	v_fma_f32 v4, -v13, v249, v4
	v_fma_f32 v20, -v14, v250, v20
	ds_read_b128 v[248:251], v21 offset:63312
	v_fma_f32 v0, -v41, v240, v0
	v_fma_f32 v4, -v43, v241, v4
	v_fma_f32 v20, -v44, v242, v20
	ds_read_b128 v[240:243], v21 offset:63328
	v_fma_f32 v0, -v46, v218, v0
	v_fma_f32 v4, -v47, v219, v4
	v_fma_f32 v20, -v48, v220, v20
	v_fma_f32 v214, -v49, v221, v204
	s_waitcnt lgkmcnt(2)
	v_fma_f32 v0, -v50, v244, v0
	v_fma_f32 v4, -v51, v245, v4
	v_fma_f32 v20, -v52, v246, v20
	v_fma_f32 v214, -v53, v247, v214
	ds_read_b128 v[244:247], v21 offset:63344
	s_waitcnt lgkmcnt(2)
	v_fma_f32 v0, -v54, v248, v0
	v_fma_f32 v4, -v55, v249, v4
	v_fma_f32 v20, -v56, v250, v20
	v_fma_f32 v214, -v57, v251, v214
	ds_read_b128 v[248:251], v21 offset:63360
	s_waitcnt lgkmcnt(2)
	v_fma_f32 v0, -v58, v240, v0
	v_fma_f32 v4, -v59, v241, v4
	v_fma_f32 v20, -v60, v242, v20
	v_fma_f32 v214, -v61, v243, v214
	ds_read_b128 v[240:243], v21 offset:63376
	s_waitcnt lgkmcnt(2)
	v_fma_f32 v0, -v62, v244, v0
	v_fma_f32 v4, -v63, v245, v4
	v_fma_f32 v20, -v64, v246, v20
	v_fma_f32 v214, -v65, v247, v214
	ds_read_b128 v[244:247], v21 offset:63392
	s_waitcnt lgkmcnt(2)
	v_fma_f32 v0, -v66, v248, v0
	v_fma_f32 v4, -v67, v249, v4
	v_fma_f32 v20, -v68, v250, v20
	v_fma_f32 v214, -v69, v251, v214
	ds_read_b128 v[248:251], v21 offset:63408
	s_waitcnt lgkmcnt(2)
	v_fma_f32 v0, -v184, v240, v0
	v_fma_f32 v4, -v185, v241, v4
	v_fma_f32 v20, -v186, v242, v20
	v_fma_f32 v214, -v187, v243, v214
	ds_read_b128 v[240:243], v21 offset:63424
	s_waitcnt lgkmcnt(2)
	v_fma_f32 v0, -v188, v244, v0
	v_fma_f32 v4, -v189, v245, v4
	v_fma_f32 v20, -v190, v246, v20
	v_fma_f32 v214, -v191, v247, v214
	ds_read_b128 v[244:247], v21 offset:63488
	s_waitcnt lgkmcnt(2)
	v_fma_f32 v0, -v192, v248, v0
	v_fma_f32 v4, -v193, v249, v4
	v_fma_f32 v20, -v194, v250, v20
	v_fma_f32 v214, -v195, v251, v214
	ds_read_b128 v[248:251], v21 offset:63504
	s_waitcnt lgkmcnt(2)
	v_fma_f32 v0, -v196, v240, v0
	v_fma_f32 v4, -v197, v241, v4
	v_fma_f32 v20, -v198, v242, v20
	v_fma_f32 v200, -v199, v243, v214
	ds_read_b128 v[240:243], v21 offset:63520
	v_add_f32_e32 v0, v0, v4
	v_add_f32_e32 v4, v20, v200
	v_add_f32_e32 v200, v0, v4
	v_mul_f32_e32 v0, v253, v223
	v_mul_f32_e32 v1, v0, v235
	v_cndmask_b32_e64 v0, v0, v1, s[26:27]
	s_waitcnt lgkmcnt(2)
	v_fma_f32 v0, -v8, v244, v0
	v_fma_f32 v1, -v9, v245, 0
	v_fma_f32 v4, -v10, v246, 0
	v_fma_f32 v5, -v11, v247, 0
	ds_read_b128 v[244:247], v21 offset:63536
	s_waitcnt lgkmcnt(2)
	v_fma_f32 v0, -v12, v248, v0
	v_fma_f32 v1, -v13, v249, v1
	v_fma_f32 v4, -v14, v250, v4
	v_fma_f32 v5, -v15, v251, v5
	ds_read_b128 v[248:251], v21 offset:63552
	s_waitcnt lgkmcnt(2)
	v_fma_f32 v0, -v41, v240, v0
	v_fma_f32 v1, -v43, v241, v1
	v_fma_f32 v4, -v44, v242, v4
	v_fma_f32 v5, -v45, v243, v5
	ds_read_b128 v[240:243], v21 offset:63568
	s_waitcnt lgkmcnt(2)
	v_fma_f32 v0, -v46, v244, v0
	v_fma_f32 v1, -v47, v245, v1
	v_fma_f32 v4, -v48, v246, v4
	v_fma_f32 v5, -v49, v247, v5
	ds_read_b128 v[244:247], v21 offset:63584
	s_waitcnt lgkmcnt(2)
	v_fma_f32 v0, -v50, v248, v0
	v_fma_f32 v1, -v51, v249, v1
	v_fma_f32 v4, -v52, v250, v4
	v_fma_f32 v5, -v53, v251, v5
	ds_read_b128 v[248:251], v21 offset:63600
	s_waitcnt lgkmcnt(2)
	v_fma_f32 v0, -v54, v240, v0
	v_fma_f32 v1, -v55, v241, v1
	v_fma_f32 v4, -v56, v242, v4
	v_fma_f32 v5, -v57, v243, v5
	ds_read_b128 v[240:243], v21 offset:63616
	s_waitcnt lgkmcnt(2)
	v_fma_f32 v0, -v58, v244, v0
	v_fma_f32 v1, -v59, v245, v1
	v_fma_f32 v4, -v60, v246, v4
	v_fma_f32 v5, -v61, v247, v5
	ds_read_b32 v206, v21 offset:63696
	ds_read_b128 v[244:247], v21 offset:63632
	s_waitcnt lgkmcnt(3)
	v_fma_f32 v0, -v62, v248, v0
	v_fma_f32 v1, -v63, v249, v1
	v_fma_f32 v4, -v64, v250, v4
	v_fma_f32 v5, -v65, v251, v5
	ds_read_b128 v[248:251], v21 offset:63648
	s_waitcnt lgkmcnt(3)
	v_fma_f32 v0, -v66, v240, v0
	v_fma_f32 v1, -v67, v241, v1
	v_fma_f32 v4, -v68, v242, v4
	v_fma_f32 v5, -v69, v243, v5
	ds_read_b128 v[240:243], v21 offset:63664
	s_waitcnt lgkmcnt(2)
	v_fma_f32 v0, -v184, v244, v0
	v_fma_f32 v1, -v185, v245, v1
	v_fma_f32 v4, -v186, v246, v4
	v_fma_f32 v5, -v187, v247, v5
	ds_read_b128 v[244:247], v21 offset:63680
	s_waitcnt lgkmcnt(2)
	v_fma_f32 v0, -v188, v248, v0
	v_fma_f32 v1, -v189, v249, v1
	v_fma_f32 v4, -v190, v250, v4
	v_fma_f32 v5, -v191, v251, v5
	ds_read_b128 v[248:251], v21 offset:63744
	s_waitcnt lgkmcnt(2)
	v_fma_f32 v0, -v192, v240, v0
	v_fma_f32 v1, -v193, v241, v1
	v_fma_f32 v4, -v194, v242, v4
	v_fma_f32 v5, -v195, v243, v5
	ds_read_b128 v[240:243], v21 offset:63760
	s_waitcnt lgkmcnt(2)
	v_fma_f32 v20, -v196, v244, v0
	v_fma_f32 v201, -v197, v245, v1
	ds_read2_b32 v[0:1], v224 offset0:182 offset1:247
	v_fma_f32 v4, -v198, v246, v4
	v_fma_f32 v5, -v199, v247, v5
	ds_read_b128 v[244:247], v21 offset:63776
	v_fma_f32 v20, -v200, v206, v20
	v_add_f32_e32 v20, v201, v20
	s_waitcnt lgkmcnt(1)
	v_mul_f32_e32 v0, v254, v0
	v_mul_f32_e32 v2, v0, v236
	v_add_f32_e32 v4, v4, v5
	v_cndmask_b32_e64 v0, v0, v2, s[26:27]
	v_add_f32_e32 v201, v4, v20
	v_fma_f32 v0, -v8, v248, v0
	v_fma_f32 v2, -v9, v249, 0
	v_fma_f32 v4, -v10, v250, 0
	v_fma_f32 v5, -v11, v251, 0
	ds_read_b128 v[248:251], v21 offset:63792
	v_fma_f32 v0, -v12, v240, v0
	v_fma_f32 v2, -v13, v241, v2
	v_fma_f32 v4, -v14, v242, v4
	v_fma_f32 v5, -v15, v243, v5
	ds_read_b128 v[240:243], v21 offset:63808
	s_waitcnt lgkmcnt(2)
	v_fma_f32 v0, -v41, v244, v0
	v_fma_f32 v2, -v43, v245, v2
	v_fma_f32 v4, -v44, v246, v4
	v_fma_f32 v5, -v45, v247, v5
	ds_read_b128 v[244:247], v21 offset:63824
	s_waitcnt lgkmcnt(2)
	v_fma_f32 v0, -v46, v248, v0
	v_fma_f32 v2, -v47, v249, v2
	v_fma_f32 v4, -v48, v250, v4
	v_fma_f32 v5, -v49, v251, v5
	ds_read_b128 v[248:251], v21 offset:63840
	s_waitcnt lgkmcnt(2)
	v_fma_f32 v0, -v50, v240, v0
	v_fma_f32 v2, -v51, v241, v2
	v_fma_f32 v4, -v52, v242, v4
	v_fma_f32 v5, -v53, v243, v5
	ds_read_b128 v[240:243], v21 offset:63856
	s_waitcnt lgkmcnt(2)
	v_fma_f32 v0, -v54, v244, v0
	v_fma_f32 v2, -v55, v245, v2
	v_fma_f32 v4, -v56, v246, v4
	v_fma_f32 v5, -v57, v247, v5
	ds_read_b128 v[244:247], v21 offset:63872
	s_waitcnt lgkmcnt(2)
	v_fma_f32 v0, -v58, v248, v0
	v_fma_f32 v2, -v59, v249, v2
	v_fma_f32 v4, -v60, v250, v4
	v_fma_f32 v5, -v61, v251, v5
	ds_read_b128 v[248:251], v21 offset:63888
	s_waitcnt lgkmcnt(2)
	v_fma_f32 v0, -v62, v240, v0
	v_fma_f32 v2, -v63, v241, v2
	v_fma_f32 v4, -v64, v242, v4
	v_fma_f32 v5, -v65, v243, v5
	ds_read_b128 v[240:243], v21 offset:63904
	s_waitcnt lgkmcnt(2)
	v_fma_f32 v0, -v66, v244, v0
	v_fma_f32 v2, -v67, v245, v2
	v_fma_f32 v4, -v68, v246, v4
	v_fma_f32 v5, -v69, v247, v5
	ds_read_b128 v[244:247], v21 offset:63920
	s_waitcnt lgkmcnt(2)
	v_fma_f32 v0, -v184, v248, v0
	v_fma_f32 v2, -v185, v249, v2
	v_fma_f32 v4, -v186, v250, v4
	v_fma_f32 v5, -v187, v251, v5
	ds_read_b128 v[248:251], v21 offset:63936
	s_waitcnt lgkmcnt(2)
	v_fma_f32 v0, -v188, v240, v0
	v_fma_f32 v2, -v189, v241, v2
	v_fma_f32 v4, -v190, v242, v4
	v_fma_f32 v5, -v191, v243, v5
	ds_read_b128 v[240:243], v21 offset:64000
	s_waitcnt lgkmcnt(2)
	v_fma_f32 v6, -v194, v246, v4
	v_fma_f32 v20, -v195, v247, v5
	ds_read_b64 v[4:5], v21 offset:63952
	v_fma_f32 v0, -v192, v244, v0
	v_fma_f32 v2, -v193, v245, v2
	ds_read_b128 v[244:247], v21 offset:64016
	s_waitcnt lgkmcnt(3)
	v_fma_f32 v0, -v196, v248, v0
	v_fma_f32 v2, -v197, v249, v2
	v_fma_f32 v6, -v198, v250, v6
	v_fma_f32 v20, -v199, v251, v20
	ds_read_b128 v[248:251], v21 offset:64032
	s_waitcnt lgkmcnt(2)
	v_fma_f32 v0, -v200, v4, v0
	v_fma_f32 v2, -v201, v5, v2
	v_add_f32_e32 v0, v0, v2
	v_add_f32_e32 v2, v6, v20
	v_add_f32_e32 v202, v2, v0
	v_mul_f32_e32 v0, v255, v1
	ds_read_b128 v[252:255], v21 offset:64048
	v_mul_f32_e32 v1, v0, v237
	ds_read_b128 v[234:237], v21 offset:64064
	v_cndmask_b32_e64 v0, v0, v1, s[26:27]
	v_fma_f32 v20, -v8, v240, v0
	v_fma_f32 v203, -v9, v241, 0
	v_fma_f32 v204, -v10, v242, 0
	v_fma_f32 v205, -v11, v243, 0
	ds_read_b128 v[240:243], v21 offset:64080
	s_waitcnt lgkmcnt(4)
	v_fma_f32 v0, -v12, v244, v20
	v_fma_f32 v20, -v13, v245, v203
	v_fma_f32 v203, -v14, v246, v204
	v_fma_f32 v204, -v15, v247, v205
	ds_read_b128 v[244:247], v21 offset:64096
	s_waitcnt lgkmcnt(4)
	v_fma_f32 v205, -v41, v248, v0
	v_fma_f32 v20, -v43, v249, v20
	v_fma_f32 v203, -v44, v250, v203
	v_fma_f32 v204, -v45, v251, v204
	ds_read_b128 v[248:251], v21 offset:64112
	s_waitcnt lgkmcnt(4)
	v_fma_f32 v0, -v46, v252, v205
	v_fma_f32 v20, -v47, v253, v20
	v_fma_f32 v203, -v48, v254, v203
	v_fma_f32 v204, -v49, v255, v204
	ds_read_b128 v[252:255], v21 offset:64128
	s_waitcnt lgkmcnt(4)
	v_fma_f32 v205, -v50, v234, v0
	v_fma_f32 v20, -v51, v235, v20
	v_fma_f32 v203, -v52, v236, v203
	v_fma_f32 v204, -v53, v237, v204
	ds_read_b128 v[234:237], v21 offset:64144
	s_waitcnt lgkmcnt(4)
	v_fma_f32 v0, -v54, v240, v205
	v_fma_f32 v20, -v55, v241, v20
	v_fma_f32 v203, -v56, v242, v203
	v_fma_f32 v204, -v57, v243, v204
	ds_read_b128 v[240:243], v21 offset:64160
	s_waitcnt lgkmcnt(4)
	v_fma_f32 v205, -v58, v244, v0
	v_fma_f32 v20, -v59, v245, v20
	v_fma_f32 v203, -v60, v246, v203
	v_fma_f32 v204, -v61, v247, v204
	ds_read_b128 v[244:247], v21 offset:64176
	s_waitcnt lgkmcnt(4)
	v_fma_f32 v0, -v62, v248, v205
	v_fma_f32 v20, -v63, v249, v20
	v_fma_f32 v203, -v64, v250, v203
	v_fma_f32 v204, -v65, v251, v204
	ds_read_b128 v[248:251], v21 offset:64192
	s_waitcnt lgkmcnt(4)
	v_fma_f32 v205, -v66, v252, v0
	v_fma_f32 v20, -v67, v253, v20
	v_fma_f32 v203, -v68, v254, v203
	v_fma_f32 v204, -v69, v255, v204
	ds_read_b128 v[252:255], v123
	s_waitcnt lgkmcnt(4)
	v_fma_f32 v0, -v184, v234, v205
	v_fma_f32 v20, -v185, v235, v20
	ds_read_b128 v[222:225], v21 offset:64304
	v_fma_f32 v203, -v186, v236, v203
	v_fma_f32 v204, -v187, v237, v204
	ds_read_b128 v[234:237], v124
	s_waitcnt lgkmcnt(5)
	v_fma_f32 v205, -v188, v240, v0
	ds_read_b96 v[0:2], v21 offset:64208
	v_fma_f32 v20, -v189, v241, v20
	v_fma_f32 v203, -v190, v242, v203
	v_fma_f32 v204, -v191, v243, v204
	ds_read_b128 v[240:243], v21 offset:64256
	s_waitcnt lgkmcnt(6)
	v_fma_f32 v205, -v192, v244, v205
	v_fma_f32 v20, -v193, v245, v20
	v_fma_f32 v203, -v194, v246, v203
	v_fma_f32 v3, -v195, v247, v204
	ds_read_b128 v[244:247], v21 offset:64272
	s_waitcnt lgkmcnt(6)
	v_fma_f32 v4, -v196, v248, v205
	v_fma_f32 v5, -v197, v249, v20
	v_fma_f32 v6, -v198, v250, v203
	v_add_u32_e32 v228, 0x3800, v88
	ds_read2_b32 v[226:227], v228 offset0:56 offset1:121
	v_fma_f32 v20, -v199, v251, v3
	ds_read_b128 v[248:251], v21 offset:64288
	s_waitcnt lgkmcnt(4)
	v_fma_f32 v203, -v200, v0, v4
	v_fma_f32 v204, -v201, v1, v5
	v_fma_f32 v205, -v202, v2, v6
	v_add_f32_e32 v203, v203, v204
	v_add_f32_e32 v20, v20, v205
	s_waitcnt lgkmcnt(1)
	v_mul_f32_e32 v0, v226, v252
	v_mul_f32_e32 v4, v0, v234
	v_cndmask_b32_e64 v0, v0, v4, s[26:27]
	v_fma_f32 v0, -v8, v240, v0
	v_fma_f32 v204, -v11, v243, 0
	v_fma_f32 v204, -v15, v247, v204
	v_add_f32_e32 v203, v203, v20
	v_fma_f32 v4, -v9, v241, 0
	v_fma_f32 v20, -v10, v242, 0
	ds_read_b128 v[240:243], v21 offset:64320
	v_fma_f32 v0, -v12, v244, v0
	s_waitcnt lgkmcnt(1)
	v_fma_f32 v214, -v45, v251, v204
	v_fma_f32 v4, -v13, v245, v4
	v_fma_f32 v20, -v14, v246, v20
	ds_read_b128 v[244:247], v21 offset:64336
	v_fma_f32 v0, -v41, v248, v0
	v_fma_f32 v218, -v49, v225, v214
	v_fma_f32 v4, -v43, v249, v4
	v_fma_f32 v20, -v44, v250, v20
	ds_read_b128 v[248:251], v21 offset:64352
	v_fma_f32 v0, -v46, v222, v0
	v_fma_f32 v4, -v47, v223, v4
	v_fma_f32 v20, -v48, v224, v20
	s_waitcnt lgkmcnt(2)
	v_fma_f32 v0, -v50, v240, v0
	v_fma_f32 v4, -v51, v241, v4
	v_fma_f32 v20, -v52, v242, v20
	v_fma_f32 v218, -v53, v243, v218
	ds_read_b128 v[240:243], v21 offset:64368
	s_waitcnt lgkmcnt(2)
	v_fma_f32 v0, -v54, v244, v0
	v_fma_f32 v4, -v55, v245, v4
	v_fma_f32 v20, -v56, v246, v20
	v_fma_f32 v218, -v57, v247, v218
	ds_read_b128 v[244:247], v21 offset:64384
	s_waitcnt lgkmcnt(2)
	v_fma_f32 v0, -v58, v248, v0
	v_fma_f32 v4, -v59, v249, v4
	v_fma_f32 v20, -v60, v250, v20
	v_fma_f32 v218, -v61, v251, v218
	ds_read_b128 v[248:251], v21 offset:64400
	s_waitcnt lgkmcnt(2)
	v_fma_f32 v0, -v62, v240, v0
	v_fma_f32 v4, -v63, v241, v4
	v_fma_f32 v20, -v64, v242, v20
	v_fma_f32 v218, -v65, v243, v218
	ds_read_b128 v[240:243], v21 offset:64416
	s_waitcnt lgkmcnt(2)
	v_fma_f32 v0, -v66, v244, v0
	v_fma_f32 v4, -v67, v245, v4
	v_fma_f32 v20, -v68, v246, v20
	v_fma_f32 v218, -v69, v247, v218
	ds_read_b128 v[244:247], v21 offset:64432
	s_waitcnt lgkmcnt(2)
	v_fma_f32 v0, -v184, v248, v0
	v_fma_f32 v4, -v185, v249, v4
	v_fma_f32 v20, -v186, v250, v20
	v_fma_f32 v218, -v187, v251, v218
	ds_read_b128 v[248:251], v21 offset:64448
	s_waitcnt lgkmcnt(2)
	v_fma_f32 v0, -v188, v240, v0
	v_fma_f32 v4, -v189, v241, v4
	v_fma_f32 v20, -v190, v242, v20
	v_fma_f32 v218, -v191, v243, v218
	ds_read_b128 v[240:243], v21 offset:64464
	s_waitcnt lgkmcnt(2)
	v_fma_f32 v0, -v192, v244, v0
	v_fma_f32 v4, -v193, v245, v4
	v_fma_f32 v20, -v194, v246, v20
	v_fma_f32 v218, -v195, v247, v218
	ds_read_b128 v[244:247], v21 offset:64512
	s_waitcnt lgkmcnt(2)
	v_fma_f32 v0, -v196, v248, v0
	v_fma_f32 v4, -v197, v249, v4
	v_fma_f32 v20, -v198, v250, v20
	v_fma_f32 v204, -v199, v251, v218
	ds_read_b128 v[248:251], v21 offset:64528
	s_waitcnt lgkmcnt(2)
	v_fma_f32 v0, -v200, v240, v0
	v_fma_f32 v4, -v201, v241, v4
	v_fma_f32 v20, -v202, v242, v20
	v_fma_f32 v204, -v203, v243, v204
	ds_read_b128 v[240:243], v21 offset:64544
	v_add_f32_e32 v0, v0, v4
	v_add_f32_e32 v4, v20, v204
	v_add_f32_e32 v204, v0, v4
	v_mul_f32_e32 v0, v253, v227
	v_mul_f32_e32 v1, v0, v235
	v_cndmask_b32_e64 v0, v0, v1, s[26:27]
	s_waitcnt lgkmcnt(2)
	v_fma_f32 v0, -v8, v244, v0
	v_fma_f32 v1, -v9, v245, 0
	v_fma_f32 v4, -v10, v246, 0
	v_fma_f32 v5, -v11, v247, 0
	ds_read_b128 v[244:247], v21 offset:64560
	s_waitcnt lgkmcnt(2)
	v_fma_f32 v0, -v12, v248, v0
	v_fma_f32 v1, -v13, v249, v1
	v_fma_f32 v4, -v14, v250, v4
	v_fma_f32 v5, -v15, v251, v5
	ds_read_b128 v[248:251], v21 offset:64576
	s_waitcnt lgkmcnt(2)
	v_fma_f32 v0, -v41, v240, v0
	v_fma_f32 v1, -v43, v241, v1
	v_fma_f32 v4, -v44, v242, v4
	v_fma_f32 v5, -v45, v243, v5
	ds_read_b128 v[240:243], v21 offset:64592
	s_waitcnt lgkmcnt(2)
	v_fma_f32 v0, -v46, v244, v0
	v_fma_f32 v1, -v47, v245, v1
	v_fma_f32 v4, -v48, v246, v4
	v_fma_f32 v5, -v49, v247, v5
	ds_read_b128 v[244:247], v21 offset:64608
	s_waitcnt lgkmcnt(2)
	v_fma_f32 v0, -v50, v248, v0
	v_fma_f32 v1, -v51, v249, v1
	v_fma_f32 v4, -v52, v250, v4
	v_fma_f32 v5, -v53, v251, v5
	ds_read_b128 v[248:251], v21 offset:64624
	s_waitcnt lgkmcnt(2)
	v_fma_f32 v0, -v54, v240, v0
	v_fma_f32 v1, -v55, v241, v1
	v_fma_f32 v4, -v56, v242, v4
	v_fma_f32 v5, -v57, v243, v5
	ds_read_b128 v[240:243], v21 offset:64640
	s_waitcnt lgkmcnt(2)
	v_fma_f32 v0, -v58, v244, v0
	v_fma_f32 v1, -v59, v245, v1
	v_fma_f32 v4, -v60, v246, v4
	v_fma_f32 v5, -v61, v247, v5
	ds_read_b128 v[244:247], v21 offset:64656
	s_waitcnt lgkmcnt(2)
	v_fma_f32 v0, -v62, v248, v0
	v_fma_f32 v1, -v63, v249, v1
	v_fma_f32 v4, -v64, v250, v4
	v_fma_f32 v5, -v65, v251, v5
	ds_read_b32 v206, v21 offset:64736
	ds_read_b128 v[248:251], v21 offset:64672
	s_waitcnt lgkmcnt(3)
	v_fma_f32 v0, -v66, v240, v0
	v_fma_f32 v1, -v67, v241, v1
	v_fma_f32 v4, -v68, v242, v4
	v_fma_f32 v5, -v69, v243, v5
	ds_read_b128 v[240:243], v21 offset:64688
	s_waitcnt lgkmcnt(3)
	v_fma_f32 v0, -v184, v244, v0
	v_fma_f32 v1, -v185, v245, v1
	v_fma_f32 v4, -v186, v246, v4
	v_fma_f32 v5, -v187, v247, v5
	ds_read_b128 v[244:247], v21 offset:64704
	s_waitcnt lgkmcnt(2)
	v_fma_f32 v0, -v188, v248, v0
	v_fma_f32 v1, -v189, v249, v1
	v_fma_f32 v4, -v190, v250, v4
	v_fma_f32 v5, -v191, v251, v5
	ds_read_b128 v[248:251], v21 offset:64720
	s_waitcnt lgkmcnt(2)
	v_fma_f32 v0, -v192, v240, v0
	v_fma_f32 v1, -v193, v241, v1
	v_fma_f32 v4, -v194, v242, v4
	v_fma_f32 v5, -v195, v243, v5
	ds_read_b128 v[240:243], v21 offset:64768
	s_waitcnt lgkmcnt(2)
	v_fma_f32 v0, -v196, v244, v0
	v_fma_f32 v1, -v197, v245, v1
	v_fma_f32 v4, -v198, v246, v4
	v_fma_f32 v5, -v199, v247, v5
	ds_read_b128 v[244:247], v21 offset:64784
	s_waitcnt lgkmcnt(2)
	v_fma_f32 v20, -v200, v248, v0
	v_fma_f32 v205, -v201, v249, v1
	ds_read2_b32 v[0:1], v228 offset0:186 offset1:251
	v_fma_f32 v4, -v202, v250, v4
	v_fma_f32 v5, -v203, v251, v5
	ds_read_b128 v[248:251], v21 offset:64800
	v_add_f32_e32 v4, v4, v5
	s_waitcnt lgkmcnt(1)
	v_mul_f32_e32 v0, v254, v0
	v_fma_f32 v20, -v204, v206, v20
	v_mul_f32_e32 v2, v0, v236
	v_add_f32_e32 v20, v205, v20
	v_cndmask_b32_e64 v0, v0, v2, s[26:27]
	v_add_f32_e32 v205, v4, v20
	v_fma_f32 v0, -v8, v240, v0
	v_fma_f32 v2, -v9, v241, 0
	v_fma_f32 v4, -v10, v242, 0
	v_fma_f32 v5, -v11, v243, 0
	ds_read_b128 v[240:243], v21 offset:64816
	v_fma_f32 v0, -v12, v244, v0
	v_fma_f32 v2, -v13, v245, v2
	v_fma_f32 v4, -v14, v246, v4
	v_fma_f32 v5, -v15, v247, v5
	ds_read_b128 v[244:247], v21 offset:64832
	s_waitcnt lgkmcnt(2)
	v_fma_f32 v0, -v41, v248, v0
	v_fma_f32 v2, -v43, v249, v2
	v_fma_f32 v4, -v44, v250, v4
	v_fma_f32 v5, -v45, v251, v5
	ds_read_b128 v[248:251], v21 offset:64848
	s_waitcnt lgkmcnt(2)
	v_fma_f32 v0, -v46, v240, v0
	v_fma_f32 v2, -v47, v241, v2
	v_fma_f32 v4, -v48, v242, v4
	v_fma_f32 v5, -v49, v243, v5
	ds_read_b128 v[240:243], v21 offset:64864
	s_waitcnt lgkmcnt(2)
	v_fma_f32 v0, -v50, v244, v0
	v_fma_f32 v2, -v51, v245, v2
	v_fma_f32 v4, -v52, v246, v4
	v_fma_f32 v5, -v53, v247, v5
	ds_read_b128 v[244:247], v21 offset:64880
	s_waitcnt lgkmcnt(2)
	v_fma_f32 v0, -v54, v248, v0
	v_fma_f32 v2, -v55, v249, v2
	v_fma_f32 v4, -v56, v250, v4
	v_fma_f32 v5, -v57, v251, v5
	ds_read_b128 v[248:251], v21 offset:64896
	s_waitcnt lgkmcnt(2)
	v_fma_f32 v0, -v58, v240, v0
	v_fma_f32 v2, -v59, v241, v2
	v_fma_f32 v4, -v60, v242, v4
	v_fma_f32 v5, -v61, v243, v5
	ds_read_b128 v[240:243], v21 offset:64912
	s_waitcnt lgkmcnt(2)
	v_fma_f32 v0, -v62, v244, v0
	v_fma_f32 v2, -v63, v245, v2
	v_fma_f32 v4, -v64, v246, v4
	v_fma_f32 v5, -v65, v247, v5
	ds_read_b128 v[244:247], v21 offset:64928
	s_waitcnt lgkmcnt(2)
	v_fma_f32 v0, -v66, v248, v0
	v_fma_f32 v2, -v67, v249, v2
	v_fma_f32 v4, -v68, v250, v4
	v_fma_f32 v5, -v69, v251, v5
	ds_read_b128 v[248:251], v21 offset:64944
	s_waitcnt lgkmcnt(2)
	v_fma_f32 v0, -v184, v240, v0
	v_fma_f32 v2, -v185, v241, v2
	v_fma_f32 v4, -v186, v242, v4
	v_fma_f32 v5, -v187, v243, v5
	ds_read_b128 v[240:243], v21 offset:64960
	s_waitcnt lgkmcnt(2)
	v_fma_f32 v0, -v188, v244, v0
	v_fma_f32 v2, -v189, v245, v2
	v_fma_f32 v4, -v190, v246, v4
	v_fma_f32 v5, -v191, v247, v5
	ds_read_b128 v[244:247], v21 offset:64976
	s_waitcnt lgkmcnt(2)
	v_fma_f32 v0, -v192, v248, v0
	v_fma_f32 v2, -v193, v249, v2
	v_fma_f32 v4, -v194, v250, v4
	v_fma_f32 v5, -v195, v251, v5
	ds_read_b128 v[248:251], v21 offset:65024
	s_waitcnt lgkmcnt(2)
	v_fma_f32 v6, -v198, v242, v4
	v_fma_f32 v20, -v199, v243, v5
	ds_read_b64 v[4:5], v21 offset:64992
	v_fma_f32 v0, -v196, v240, v0
	v_fma_f32 v2, -v197, v241, v2
	ds_read_b128 v[240:243], v21 offset:65040
	s_waitcnt lgkmcnt(3)
	v_fma_f32 v0, -v200, v244, v0
	v_fma_f32 v2, -v201, v245, v2
	v_fma_f32 v6, -v202, v246, v6
	v_fma_f32 v20, -v203, v247, v20
	ds_read_b128 v[244:247], v21 offset:65056
	s_waitcnt lgkmcnt(2)
	v_fma_f32 v0, -v204, v4, v0
	v_fma_f32 v2, -v205, v5, v2
	v_add_f32_e32 v0, v0, v2
	v_add_f32_e32 v2, v6, v20
	v_add_f32_e32 v206, v2, v0
	v_mul_f32_e32 v0, v255, v1
	ds_read_b128 v[252:255], v21 offset:65072
	v_mul_f32_e32 v1, v0, v237
	ds_read_b128 v[234:237], v21 offset:65088
	v_cndmask_b32_e64 v4, v0, v1, s[26:27]
	v_fma_f32 v4, -v8, v248, v4
	v_fma_f32 v20, -v9, v249, 0
	v_fma_f32 v207, -v10, v250, 0
	v_fma_f32 v214, -v11, v251, 0
	ds_read_b128 v[248:251], v21 offset:65104
	s_waitcnt lgkmcnt(4)
	v_fma_f32 v215, -v12, v240, v4
	v_fma_f32 v20, -v13, v241, v20
	v_fma_f32 v207, -v14, v242, v207
	v_fma_f32 v214, -v15, v243, v214
	ds_read_b128 v[240:243], v21 offset:65120
	s_waitcnt lgkmcnt(4)
	v_fma_f32 v4, -v41, v244, v215
	v_fma_f32 v20, -v43, v245, v20
	v_fma_f32 v207, -v44, v246, v207
	v_fma_f32 v214, -v45, v247, v214
	ds_read_b128 v[244:247], v21 offset:65136
	s_waitcnt lgkmcnt(4)
	v_fma_f32 v215, -v46, v252, v4
	v_fma_f32 v20, -v47, v253, v20
	v_fma_f32 v207, -v48, v254, v207
	v_fma_f32 v214, -v49, v255, v214
	ds_read_b128 v[252:255], v21 offset:65152
	s_waitcnt lgkmcnt(4)
	v_fma_f32 v4, -v50, v234, v215
	v_fma_f32 v20, -v51, v235, v20
	v_fma_f32 v207, -v52, v236, v207
	v_fma_f32 v214, -v53, v237, v214
	ds_read_b128 v[234:237], v21 offset:65168
	s_waitcnt lgkmcnt(4)
	v_fma_f32 v215, -v54, v248, v4
	v_fma_f32 v20, -v55, v249, v20
	v_fma_f32 v207, -v56, v250, v207
	v_fma_f32 v214, -v57, v251, v214
	ds_read_b128 v[248:251], v21 offset:65184
	s_waitcnt lgkmcnt(4)
	v_fma_f32 v4, -v58, v240, v215
	v_fma_f32 v20, -v59, v241, v20
	v_fma_f32 v207, -v60, v242, v207
	v_fma_f32 v214, -v61, v243, v214
	ds_read_b128 v[240:243], v21 offset:65200
	s_waitcnt lgkmcnt(4)
	v_fma_f32 v215, -v62, v244, v4
	v_fma_f32 v20, -v63, v245, v20
	v_fma_f32 v207, -v64, v246, v207
	v_fma_f32 v214, -v65, v247, v214
	ds_read_b128 v[244:247], v21 offset:65216
	s_waitcnt lgkmcnt(4)
	v_fma_f32 v4, -v66, v252, v215
	v_fma_f32 v20, -v67, v253, v20
	v_fma_f32 v207, -v68, v254, v207
	v_fma_f32 v214, -v69, v255, v214
	ds_read_b128 v[252:255], v21 offset:65232
	s_waitcnt lgkmcnt(4)
	v_fma_f32 v215, -v184, v234, v4
	v_fma_f32 v20, -v185, v235, v20
	v_fma_f32 v207, -v186, v236, v207
	v_fma_f32 v214, -v187, v237, v214
	ds_read_b128 v[234:237], v125
	s_waitcnt lgkmcnt(4)
	v_fma_f32 v4, -v188, v248, v215
	v_fma_f32 v20, -v189, v249, v20
	ds_read_b128 v[226:229], v21 offset:65328
	v_fma_f32 v207, -v190, v250, v207
	v_fma_f32 v214, -v191, v251, v214
	ds_read_b128 v[248:251], v126
	s_waitcnt lgkmcnt(5)
	v_fma_f32 v215, -v192, v240, v4
	ds_read_b96 v[4:6], v21 offset:65248
	v_fma_f32 v20, -v193, v241, v20
	v_fma_f32 v207, -v194, v242, v207
	v_fma_f32 v214, -v195, v243, v214
	ds_read_b128 v[240:243], v21 offset:65280
	s_waitcnt lgkmcnt(6)
	v_fma_f32 v215, -v196, v244, v215
	v_fma_f32 v20, -v197, v245, v20
	v_fma_f32 v207, -v198, v246, v207
	v_fma_f32 v7, -v199, v247, v214
	ds_read_b128 v[244:247], v21 offset:65296
	s_waitcnt lgkmcnt(6)
	v_fma_f32 v0, -v200, v252, v215
	v_fma_f32 v1, -v201, v253, v20
	v_fma_f32 v2, -v202, v254, v207
	v_add_u32_e32 v232, 0x3c00, v88
	ds_read2_b32 v[230:231], v232 offset0:60 offset1:125
	v_fma_f32 v20, -v203, v255, v7
	ds_read_b128 v[252:255], v21 offset:65312
	s_waitcnt lgkmcnt(4)
	v_fma_f32 v207, -v204, v4, v0
	v_fma_f32 v214, -v205, v5, v1
	v_fma_f32 v215, -v206, v6, v2
	v_add_f32_e32 v207, v207, v214
	v_add_f32_e32 v20, v20, v215
	s_waitcnt lgkmcnt(1)
	v_mul_f32_e32 v0, v230, v234
	v_mul_f32_e32 v4, v0, v248
	v_cndmask_b32_e64 v0, v0, v4, s[26:27]
	v_fma_f32 v0, -v8, v240, v0
	v_fma_f32 v214, -v11, v243, 0
	v_fma_f32 v214, -v15, v247, v214
	v_add_f32_e32 v207, v207, v20
	v_fma_f32 v4, -v9, v241, 0
	v_fma_f32 v20, -v10, v242, 0
	ds_read_b128 v[240:243], v21 offset:65344
	v_fma_f32 v0, -v12, v244, v0
	s_waitcnt lgkmcnt(1)
	v_fma_f32 v218, -v45, v255, v214
	v_fma_f32 v4, -v13, v245, v4
	v_fma_f32 v20, -v14, v246, v20
	ds_read_b128 v[244:247], v21 offset:65360
	v_fma_f32 v0, -v41, v252, v0
	v_fma_f32 v4, -v43, v253, v4
	v_fma_f32 v20, -v44, v254, v20
	ds_read_b128 v[252:255], v21 offset:65376
	v_fma_f32 v0, -v46, v226, v0
	v_fma_f32 v4, -v47, v227, v4
	v_fma_f32 v20, -v48, v228, v20
	v_fma_f32 v222, -v49, v229, v218
	s_waitcnt lgkmcnt(2)
	v_fma_f32 v0, -v50, v240, v0
	v_fma_f32 v4, -v51, v241, v4
	v_fma_f32 v20, -v52, v242, v20
	v_fma_f32 v222, -v53, v243, v222
	ds_read_b128 v[240:243], v21 offset:65392
	s_waitcnt lgkmcnt(2)
	v_fma_f32 v0, -v54, v244, v0
	v_fma_f32 v4, -v55, v245, v4
	v_fma_f32 v20, -v56, v246, v20
	v_fma_f32 v222, -v57, v247, v222
	ds_read_b128 v[244:247], v21 offset:65408
	s_waitcnt lgkmcnt(2)
	v_fma_f32 v0, -v58, v252, v0
	v_fma_f32 v4, -v59, v253, v4
	v_fma_f32 v20, -v60, v254, v20
	v_fma_f32 v222, -v61, v255, v222
	ds_read_b128 v[252:255], v21 offset:65424
	s_waitcnt lgkmcnt(2)
	v_fma_f32 v0, -v62, v240, v0
	v_fma_f32 v4, -v63, v241, v4
	v_fma_f32 v20, -v64, v242, v20
	v_fma_f32 v222, -v65, v243, v222
	ds_read_b128 v[240:243], v21 offset:65440
	s_waitcnt lgkmcnt(2)
	v_fma_f32 v0, -v66, v244, v0
	v_fma_f32 v4, -v67, v245, v4
	v_fma_f32 v20, -v68, v246, v20
	v_fma_f32 v222, -v69, v247, v222
	ds_read_b128 v[244:247], v21 offset:65456
	s_waitcnt lgkmcnt(2)
	v_fma_f32 v0, -v184, v252, v0
	v_fma_f32 v4, -v185, v253, v4
	v_fma_f32 v20, -v186, v254, v20
	v_fma_f32 v222, -v187, v255, v222
	ds_read_b128 v[252:255], v21 offset:65472
	s_waitcnt lgkmcnt(2)
	v_fma_f32 v0, -v188, v240, v0
	v_fma_f32 v4, -v189, v241, v4
	v_fma_f32 v20, -v190, v242, v20
	v_fma_f32 v222, -v191, v243, v222
	ds_read_b128 v[240:243], v21 offset:65488
	s_waitcnt lgkmcnt(2)
	v_fma_f32 v0, -v192, v244, v0
	v_fma_f32 v4, -v193, v245, v4
	v_fma_f32 v20, -v194, v246, v20
	v_fma_f32 v222, -v195, v247, v222
	ds_read_b128 v[244:247], v21 offset:65504
	s_waitcnt lgkmcnt(2)
	v_fma_f32 v0, -v196, v252, v0
	v_fma_f32 v4, -v197, v253, v4
	v_fma_f32 v20, -v198, v254, v20
	v_fma_f32 v222, -v199, v255, v222
	ds_read_b128 v[252:255], v127
	s_waitcnt lgkmcnt(2)
	v_fma_f32 v0, -v200, v240, v0
	v_fma_f32 v4, -v201, v241, v4
	v_fma_f32 v20, -v202, v242, v20
	v_fma_f32 v218, -v203, v243, v222
	ds_read_b128 v[240:243], v128
	s_waitcnt lgkmcnt(2)
	v_fma_f32 v0, -v204, v244, v0
	v_fma_f32 v4, -v205, v245, v4
	v_fma_f32 v20, -v206, v246, v20
	v_fma_f32 v214, -v207, v247, v218
	ds_read_b128 v[244:247], v129
	v_add_f32_e32 v0, v0, v4
	v_add_f32_e32 v4, v20, v214
	v_mul_f32_e32 v1, v235, v231
	v_add_f32_e32 v0, v0, v4
	v_mul_f32_e32 v4, v1, v249
	v_cndmask_b32_e64 v1, v1, v4, s[26:27]
	s_waitcnt lgkmcnt(2)
	v_fma_f32 v1, -v8, v252, v1
	v_fma_f32 v4, -v9, v253, 0
	v_fma_f32 v5, -v10, v254, 0
	v_fma_f32 v20, -v11, v255, 0
	ds_read_b128 v[252:255], v130
	s_waitcnt lgkmcnt(2)
	v_fma_f32 v1, -v12, v240, v1
	v_fma_f32 v4, -v13, v241, v4
	v_fma_f32 v5, -v14, v242, v5
	v_fma_f32 v20, -v15, v243, v20
	ds_read_b128 v[240:243], v131
	s_waitcnt lgkmcnt(2)
	v_fma_f32 v1, -v41, v244, v1
	v_fma_f32 v4, -v43, v245, v4
	v_fma_f32 v5, -v44, v246, v5
	v_fma_f32 v20, -v45, v247, v20
	ds_read_b128 v[244:247], v132
	s_waitcnt lgkmcnt(2)
	v_fma_f32 v1, -v46, v252, v1
	v_fma_f32 v4, -v47, v253, v4
	v_fma_f32 v5, -v48, v254, v5
	v_fma_f32 v20, -v49, v255, v20
	ds_read_b128 v[252:255], v133
	s_waitcnt lgkmcnt(2)
	v_fma_f32 v1, -v50, v240, v1
	v_fma_f32 v4, -v51, v241, v4
	v_fma_f32 v5, -v52, v242, v5
	v_fma_f32 v20, -v53, v243, v20
	ds_read_b128 v[240:243], v134
	s_waitcnt lgkmcnt(2)
	v_fma_f32 v1, -v54, v244, v1
	v_fma_f32 v4, -v55, v245, v4
	v_fma_f32 v5, -v56, v246, v5
	v_fma_f32 v20, -v57, v247, v20
	ds_read_b128 v[244:247], v135
	s_waitcnt lgkmcnt(2)
	v_fma_f32 v1, -v58, v252, v1
	v_fma_f32 v4, -v59, v253, v4
	v_fma_f32 v5, -v60, v254, v5
	v_fma_f32 v20, -v61, v255, v20
	ds_read_b128 v[252:255], v136
	s_waitcnt lgkmcnt(2)
	v_fma_f32 v1, -v62, v240, v1
	v_fma_f32 v4, -v63, v241, v4
	v_fma_f32 v5, -v64, v242, v5
	ds_read_b32 v218, v142
	v_fma_f32 v20, -v65, v243, v20
	ds_read_b128 v[240:243], v137
	s_waitcnt lgkmcnt(3)
	v_fma_f32 v1, -v66, v244, v1
	v_fma_f32 v4, -v67, v245, v4
	v_fma_f32 v5, -v68, v246, v5
	v_fma_f32 v20, -v69, v247, v20
	ds_read_b128 v[244:247], v138
	s_waitcnt lgkmcnt(3)
	v_fma_f32 v1, -v184, v252, v1
	v_fma_f32 v4, -v185, v253, v4
	v_fma_f32 v5, -v186, v254, v5
	v_fma_f32 v20, -v187, v255, v20
	ds_read_b128 v[252:255], v139
	s_waitcnt lgkmcnt(2)
	v_fma_f32 v1, -v188, v240, v1
	v_fma_f32 v4, -v189, v241, v4
	v_fma_f32 v5, -v190, v242, v5
	v_fma_f32 v20, -v191, v243, v20
	ds_read_b128 v[240:243], v140
	s_waitcnt lgkmcnt(2)
	v_fma_f32 v1, -v192, v244, v1
	v_fma_f32 v4, -v193, v245, v4
	v_fma_f32 v5, -v194, v246, v5
	v_fma_f32 v20, -v195, v247, v20
	ds_read_b128 v[244:247], v141
	s_waitcnt lgkmcnt(2)
	v_fma_f32 v1, -v196, v252, v1
	v_fma_f32 v4, -v197, v253, v4
	v_fma_f32 v5, -v198, v254, v5
	v_fma_f32 v20, -v199, v255, v20
	ds_read_b128 v[252:255], v143
	s_waitcnt lgkmcnt(2)
	v_fma_f32 v1, -v200, v240, v1
	v_fma_f32 v4, -v201, v241, v4
	v_fma_f32 v5, -v202, v242, v5
	s_waitcnt lgkmcnt(1)
	v_fma_f32 v1, -v204, v244, v1
	v_fma_f32 v214, -v205, v245, v4
	v_fma_f32 v215, -v206, v246, v5
	ds_read2_b32 v[4:5], v232 offset0:190 offset1:255
	v_fma_f32 v20, -v203, v243, v20
	ds_read_b128 v[240:243], v144
	v_fma_f32 v20, -v207, v247, v20
	ds_read_b128 v[244:247], v145
	v_fma_f32 v1, -v0, v218, v1
	v_add_f32_e32 v1, v214, v1
	v_add_f32_e32 v20, v215, v20
	s_waitcnt lgkmcnt(2)
	v_mul_f32_e32 v2, v236, v4
	v_mul_f32_e32 v4, v2, v250
	v_cndmask_b32_e64 v2, v2, v4, s[26:27]
	v_add_f32_e32 v1, v20, v1
	v_fma_f32 v2, -v8, v252, v2
	v_fma_f32 v4, -v9, v253, 0
	v_fma_f32 v6, -v10, v254, 0
	v_fma_f32 v20, -v11, v255, 0
	ds_read_b128 v[252:255], v146
	s_waitcnt lgkmcnt(2)
	v_fma_f32 v2, -v12, v240, v2
	v_fma_f32 v4, -v13, v241, v4
	v_fma_f32 v6, -v14, v242, v6
	v_fma_f32 v20, -v15, v243, v20
	ds_read_b128 v[240:243], v147
	s_waitcnt lgkmcnt(2)
	v_fma_f32 v2, -v41, v244, v2
	v_fma_f32 v4, -v43, v245, v4
	v_fma_f32 v6, -v44, v246, v6
	v_fma_f32 v20, -v45, v247, v20
	ds_read_b128 v[244:247], v148
	s_waitcnt lgkmcnt(2)
	v_fma_f32 v2, -v46, v252, v2
	v_fma_f32 v4, -v47, v253, v4
	v_fma_f32 v6, -v48, v254, v6
	v_fma_f32 v20, -v49, v255, v20
	ds_read_b128 v[252:255], v149
	s_waitcnt lgkmcnt(2)
	v_fma_f32 v2, -v50, v240, v2
	v_fma_f32 v4, -v51, v241, v4
	v_fma_f32 v6, -v52, v242, v6
	v_fma_f32 v20, -v53, v243, v20
	ds_read_b128 v[240:243], v150
	s_waitcnt lgkmcnt(2)
	v_fma_f32 v2, -v54, v244, v2
	v_fma_f32 v4, -v55, v245, v4
	v_fma_f32 v6, -v56, v246, v6
	v_fma_f32 v20, -v57, v247, v20
	ds_read_b128 v[244:247], v151
	s_waitcnt lgkmcnt(2)
	v_fma_f32 v2, -v58, v252, v2
	v_fma_f32 v4, -v59, v253, v4
	v_fma_f32 v6, -v60, v254, v6
	v_fma_f32 v20, -v61, v255, v20
	ds_read_b128 v[252:255], v152
	s_waitcnt lgkmcnt(2)
	v_fma_f32 v2, -v62, v240, v2
	v_fma_f32 v4, -v63, v241, v4
	v_fma_f32 v6, -v64, v242, v6
	v_fma_f32 v20, -v65, v243, v20
	ds_read_b64 v[218:219], v158
	ds_read_b128 v[240:243], v153
	s_waitcnt lgkmcnt(3)
	v_fma_f32 v2, -v66, v244, v2
	v_fma_f32 v4, -v67, v245, v4
	v_fma_f32 v6, -v68, v246, v6
	v_fma_f32 v20, -v69, v247, v20
	ds_read_b128 v[244:247], v154
	s_waitcnt lgkmcnt(3)
	v_fma_f32 v2, -v184, v252, v2
	v_fma_f32 v4, -v185, v253, v4
	v_fma_f32 v6, -v186, v254, v6
	v_fma_f32 v20, -v187, v255, v20
	ds_read_b128 v[252:255], v155
	s_waitcnt lgkmcnt(2)
	v_fma_f32 v2, -v188, v240, v2
	v_fma_f32 v4, -v189, v241, v4
	v_fma_f32 v6, -v190, v242, v6
	v_fma_f32 v20, -v191, v243, v20
	ds_read_b128 v[240:243], v156
	s_waitcnt lgkmcnt(2)
	v_fma_f32 v2, -v192, v244, v2
	v_fma_f32 v4, -v193, v245, v4
	v_fma_f32 v6, -v194, v246, v6
	v_fma_f32 v20, -v195, v247, v20
	ds_read_b128 v[244:247], v157
	s_waitcnt lgkmcnt(2)
	v_fma_f32 v2, -v196, v252, v2
	v_fma_f32 v4, -v197, v253, v4
	v_fma_f32 v6, -v198, v254, v6
	v_fma_f32 v20, -v199, v255, v20
	ds_read_b128 v[252:255], v159
	s_waitcnt lgkmcnt(2)
	v_fma_f32 v2, -v200, v240, v2
	v_fma_f32 v4, -v201, v241, v4
	v_fma_f32 v6, -v202, v242, v6
	v_fma_f32 v20, -v203, v243, v20
	ds_read_b128 v[240:243], v160
	s_waitcnt lgkmcnt(2)
	v_fma_f32 v2, -v204, v244, v2
	v_fma_f32 v4, -v205, v245, v4
	v_fma_f32 v6, -v206, v246, v6
	v_fma_f32 v20, -v207, v247, v20
	ds_read_b128 v[244:247], v161
	v_fma_f32 v2, -v0, v218, v2
	v_fma_f32 v4, -v1, v219, v4
	v_add_f32_e32 v2, v2, v4
	v_add_f32_e32 v4, v6, v20
	v_mul_f32_e32 v3, v237, v5
	ds_read_b128 v[234:237], v162
	v_add_f32_e32 v2, v4, v2
	v_mul_f32_e32 v4, v3, v251
	ds_read_b128 v[248:251], v163
	v_cndmask_b32_e64 v3, v3, v4, s[26:27]
	s_waitcnt lgkmcnt(4)
	v_fma_f32 v3, -v8, v252, v3
	v_fma_f32 v20, -v9, v253, 0
	v_fma_f32 v218, -v10, v254, 0
	v_fma_f32 v219, -v11, v255, 0
	ds_read_b128 v[252:255], v164
	s_waitcnt lgkmcnt(4)
	v_fma_f32 v3, -v12, v240, v3
	v_fma_f32 v20, -v13, v241, v20
	v_fma_f32 v218, -v14, v242, v218
	v_fma_f32 v219, -v15, v243, v219
	ds_read_b128 v[240:243], v165
	s_waitcnt lgkmcnt(4)
	v_fma_f32 v3, -v41, v244, v3
	v_fma_f32 v20, -v43, v245, v20
	v_fma_f32 v218, -v44, v246, v218
	v_fma_f32 v219, -v45, v247, v219
	ds_read_b128 v[244:247], v166
	s_waitcnt lgkmcnt(4)
	v_fma_f32 v3, -v46, v234, v3
	v_fma_f32 v20, -v47, v235, v20
	v_fma_f32 v218, -v48, v236, v218
	v_fma_f32 v219, -v49, v237, v219
	ds_read_b128 v[234:237], v167
	s_waitcnt lgkmcnt(4)
	v_fma_f32 v3, -v50, v248, v3
	v_fma_f32 v20, -v51, v249, v20
	v_fma_f32 v218, -v52, v250, v218
	v_fma_f32 v219, -v53, v251, v219
	ds_read_b128 v[248:251], v168
	s_waitcnt lgkmcnt(4)
	v_fma_f32 v3, -v54, v252, v3
	v_fma_f32 v20, -v55, v253, v20
	v_fma_f32 v218, -v56, v254, v218
	v_fma_f32 v219, -v57, v255, v219
	ds_read_b128 v[252:255], v169
	s_waitcnt lgkmcnt(4)
	v_fma_f32 v3, -v58, v240, v3
	v_fma_f32 v20, -v59, v241, v20
	v_fma_f32 v218, -v60, v242, v218
	v_fma_f32 v219, -v61, v243, v219
	ds_read_b128 v[240:243], v170
	s_waitcnt lgkmcnt(4)
	v_fma_f32 v3, -v62, v244, v3
	v_fma_f32 v20, -v63, v245, v20
	ds_read_b96 v[4:6], v174
	v_fma_f32 v218, -v64, v246, v218
	v_fma_f32 v219, -v65, v247, v219
	ds_read_b128 v[244:247], v171
	s_waitcnt lgkmcnt(5)
	v_fma_f32 v3, -v66, v234, v3
	v_fma_f32 v20, -v67, v235, v20
	v_fma_f32 v218, -v68, v236, v218
	v_fma_f32 v219, -v69, v237, v219
	ds_read_b128 v[234:237], v172
	s_waitcnt lgkmcnt(5)
	v_fma_f32 v3, -v184, v248, v3
	v_fma_f32 v20, -v185, v249, v20
	v_fma_f32 v218, -v186, v250, v218
	v_fma_f32 v219, -v187, v251, v219
	ds_read_b128 v[248:251], v173
	s_waitcnt lgkmcnt(5)
	v_fma_f32 v3, -v188, v252, v3
	v_fma_f32 v20, -v189, v253, v20
	v_fma_f32 v218, -v190, v254, v218
	v_fma_f32 v219, -v191, v255, v219
	s_waitcnt lgkmcnt(4)
	v_fma_f32 v3, -v192, v240, v3
	v_fma_f32 v20, -v193, v241, v20
	v_fma_f32 v218, -v194, v242, v218
	v_fma_f32 v219, -v195, v243, v219
	s_waitcnt lgkmcnt(2)
	v_fma_f32 v3, -v196, v244, v3
	v_fma_f32 v20, -v197, v245, v20
	v_fma_f32 v218, -v198, v246, v218
	v_fma_f32 v219, -v199, v247, v219
	s_waitcnt lgkmcnt(1)
	v_fma_f32 v3, -v200, v234, v3
	v_fma_f32 v20, -v201, v235, v20
	v_fma_f32 v218, -v202, v236, v218
	v_fma_f32 v7, -v203, v237, v219
	s_waitcnt lgkmcnt(0)
	v_fma_f32 v3, -v204, v248, v3
	v_fma_f32 v20, -v205, v249, v20
	v_fma_f32 v214, -v206, v250, v218
	v_fma_f32 v7, -v207, v251, v7
	v_fma_f32 v3, -v0, v4, v3
	v_fma_f32 v4, -v1, v5, v20
	v_fma_f32 v5, -v2, v6, v214
	v_add_f32_e32 v3, v3, v4
	v_add_f32_e32 v4, v7, v5
	v_add_f32_e32 v3, v3, v4
	s_waitcnt lgkmcnt(0)
	s_and_saveexec_b64 s[28:29], s[2:3]
	s_xor_b64 s[28:29], exec, s[28:29]
	s_cbranch_execz .LBB0_3021
	v_cvt_pk_bf16_f32 v4, v8, v9
	v_cvt_pk_bf16_f32 v5, v10, v11
	v_cvt_pk_bf16_f32 v6, v12, v13
	v_cvt_pk_bf16_f32 v7, v14, v15
	global_store_dwordx4 v175, v[4:7], s[30:31]
	s_nop 1
	v_cvt_pk_bf16_f32 v4, v41, v43
	v_cvt_pk_bf16_f32 v5, v44, v45
	v_cvt_pk_bf16_f32 v6, v46, v47
	v_cvt_pk_bf16_f32 v7, v48, v49
	global_store_dwordx4 v175, v[4:7], s[30:31] offset:16
	s_nop 1
	v_cvt_pk_bf16_f32 v4, v50, v51
	v_cvt_pk_bf16_f32 v5, v52, v53
	v_cvt_pk_bf16_f32 v6, v54, v55
	v_cvt_pk_bf16_f32 v7, v56, v57
	global_store_dwordx4 v175, v[4:7], s[30:31] offset:32
	s_nop 1
	v_cvt_pk_bf16_f32 v4, v58, v59
	v_cvt_pk_bf16_f32 v5, v60, v61
	v_cvt_pk_bf16_f32 v6, v62, v63
	v_cvt_pk_bf16_f32 v7, v64, v65
	global_store_dwordx4 v175, v[4:7], s[30:31] offset:48
	s_nop 1
	v_cvt_pk_bf16_f32 v4, v66, v67
	v_cvt_pk_bf16_f32 v5, v68, v69
	v_cvt_pk_bf16_f32 v6, v184, v185
	v_cvt_pk_bf16_f32 v7, v186, v187
	global_store_dwordx4 v175, v[4:7], s[30:31] offset:64
	s_nop 1
	v_cvt_pk_bf16_f32 v4, v188, v189
	v_cvt_pk_bf16_f32 v5, v190, v191
	v_cvt_pk_bf16_f32 v6, v192, v193
	v_cvt_pk_bf16_f32 v7, v194, v195
	global_store_dwordx4 v175, v[4:7], s[30:31] offset:80
	s_nop 1
	v_cvt_pk_bf16_f32 v4, v196, v197
	v_cvt_pk_bf16_f32 v5, v198, v199
	v_cvt_pk_bf16_f32 v6, v200, v201
	v_cvt_pk_bf16_f32 v7, v202, v203
	global_store_dwordx4 v175, v[4:7], s[30:31] offset:96
	s_nop 1
	v_cvt_pk_bf16_f32 v4, v204, v205
	v_cvt_pk_bf16_f32 v5, v206, v207
	v_cvt_pk_bf16_f32 v6, v0, v1
	v_cvt_pk_bf16_f32 v7, v2, v3
	global_store_dwordx4 v175, v[4:7], s[30:31] offset:112

.LBB0_3203:
	s_cmp_eq_u32 s33, 1
	s_cbranch_scc1 .Lscan_passive
	s_mov_b32 s5, s50
	s_waitcnt vmcnt(0)
	v_and_b32_e32 v157, 0xff, v208
	s_lshr_b32 s12, s50, 3
	s_mul_i32 s4, s5, 0x28a000
	s_add_u32 s0, s60, s4
	v_or_b32_e32 v171, 0x100, v157
	s_addc_u32 s1, s61, 0
	v_lshlrev_b32_e32 v0, 4, v157
	v_lshlrev_b32_e32 v1, 4, v171
	v_or_b32_e32 v172, 0x200, v157
	v_or_b32_e32 v8, 0x300, v208
	s_barrier
	global_load_dwordx4 v[96:99], v0, s[0:1]
	global_load_dwordx4 v[100:103], v1, s[0:1]
	v_lshlrev_b32_e32 v1, 4, v172
	v_lshlrev_b32_e32 v4, 4, v8
	v_or_b32_e32 v9, 0x400, v157
	v_or_b32_e32 v10, 0x500, v157
	global_load_dwordx4 v[104:107], v4, s[0:1]
	v_lshlrev_b32_e32 v5, 4, v9
	global_load_dwordx4 v[108:111], v1, s[0:1]
	global_load_dwordx4 v[112:115], v5, s[0:1]
	v_lshlrev_b32_e32 v1, 4, v10
	v_or_b32_e32 v11, 0x600, v157
	v_or_b32_e32 v12, 0x700, v208
	v_or_b32_e32 v13, 0x800, v157
	v_lshlrev_b32_e32 v5, 4, v11
	global_load_dwordx4 v[116:119], v1, s[0:1]
	global_load_dwordx4 v[120:123], v5, s[0:1]
	v_lshlrev_b32_e32 v6, 4, v12
	v_lshlrev_b32_e32 v1, 4, v13
	v_or_b32_e32 v14, 0x900, v157
	global_load_dwordx4 v[124:127], v6, s[0:1]
	global_load_dwordx4 v[128:131], v1, s[0:1]
	v_lshlrev_b32_e32 v1, 4, v14
	global_load_dwordx4 v[132:135], v1, s[0:1]
	v_and_b32_e32 v156, 56, v3
	v_lshrrev_b32_e32 v8, 3, v8
	v_lshlrev_b32_e32 v3, 1, v156
	v_mul_u32_u24_e32 v8, 0x88, v8
	v_lshrrev_b32_e32 v9, 3, v9
	v_mul_u32_u24_e32 v15, 0x88, v170
	v_add3_u32 v175, s36, v8, v3
	v_mul_u32_u24_e32 v8, 0x88, v9
	v_lshrrev_b32_e32 v12, 3, v12
	v_add3_u32 v174, s36, v15, v3
	v_lshrrev_b32_e32 v173, 3, v171
	v_lshrrev_b32_e32 v15, 3, v172
	v_lshrrev_b32_e32 v10, 3, v10
	v_lshrrev_b32_e32 v11, 3, v11
	v_lshrrev_b32_e32 v13, 3, v13
	v_add3_u32 v179, s36, v8, v3
	v_lshrrev_b32_e32 v8, 3, v14
	s_mov_b32 s1, 0
	s_mul_i32 s0, s5, 0x41
	v_mul_u32_u24_e32 v12, 0x88, v12
	v_mul_u32_u24_e32 v16, 0x88, v173
	v_mul_u32_u24_e32 v15, 0x88, v15
	v_mul_u32_u24_e32 v9, 0x88, v10
	v_mul_u32_u24_e32 v10, 0x88, v11
	v_mul_u32_u24_e32 v11, 0x88, v13
	v_mul_u32_u24_e32 v8, 0x88, v8
	v_add3_u32 v176, s36, v12, v3
	s_lshl_b64 s[0:1], s[0:1], 2
	v_add3_u32 v177, s36, v16, v3
	v_add3_u32 v178, s36, v15, v3
	v_add3_u32 v180, s36, v9, v3
	v_add3_u32 v181, s36, v10, v3
	v_add3_u32 v182, s36, v11, v3
	v_add3_u32 v183, s36, v8, v3
	v_mbcnt_hi_u32_b32 v3, -1, v209
	s_add_u32 s0, s90, s0
	v_and_b32_e32 v9, 64, v3
	s_addc_u32 s1, s91, s1
	v_xor_b32_e32 v8, 1, v3
	v_add_u32_e32 v9, 64, v9
	s_add_u32 s0, s0, 0x13d6000
	v_cmp_lt_i32_e32 vcc, v8, v9
	s_addc_u32 s1, s1, 0
	s_lshl_b32 s5, s5, 7
	v_cndmask_b32_e32 v8, v3, v8, vcc
	v_lshlrev_b32_e32 v188, 2, v8
	v_xor_b32_e32 v8, 2, v3
	s_and_b32 s5, s5, 0x380
	v_mov_b32_e32 v1, 0
	v_and_b32_e32 v11, 48, v213
	v_cmp_lt_i32_e32 vcc, v8, v9
	s_add_u32 s6, s58, s5
	s_addc_u32 s7, s59, 0
	v_cndmask_b32_e32 v3, v3, v8, vcc
	v_lshlrev_b32_e32 v8, 1, v11
	v_mov_b32_e32 v9, v1
	v_lshl_add_u64 v[158:159], s[6:7], 0, v[8:9]
	s_add_u32 s6, s90, s5
	s_addc_u32 s7, s91, 0
	v_bfe_u32 v10, v208, 2, 6
	v_lshlrev_b32_e32 v189, 2, v3
	v_and_b32_e32 v185, 0x60, v2
	v_lshl_add_u64 v[2:3], s[6:7], 0, v[8:9]
	s_mov_b64 s[6:7], 0x241ba00
	v_or_b32_e32 v186, v185, v211
	v_and_b32_e32 v12, 4, v212
	v_lshl_add_u64 v[160:161], v[2:3], 0, s[6:7]
	v_mul_u32_u24_e32 v3, 0x104, v10
	v_lshlrev_b32_e32 v2, 2, v11
	v_readlane_b32 s16, v239, 4
	s_add_u32 s4, s90, s4
	s_movk_i32 s8, 0x88
	v_mov_b32_e32 v5, v1
	v_mov_b32_e32 v7, v1
	v_lshl_add_u32 v13, v12, 1, s36
	v_mul_u32_u24_e32 v187, 0x44, v211
	v_lshl_add_u32 v16, v186, 2, s36
	v_mul_u32_u24_e32 v17, 0x104, v12
	v_add3_u32 v192, s36, v3, v2
	v_mov_b32_e32 v3, v1
	v_readlane_b32 s17, v239, 5
	s_addc_u32 s5, s91, 0
	v_mov_b32_e32 v14, v1
	v_mov_b32_e32 v15, v1
	v_subrev_u32_e32 v184, 48, v10
	s_movk_i32 s2, 0x80
	v_mad_u32_u24 v190, v186, s8, v13
	v_lshl_add_u32 v191, v187, 1, v13
	v_readlane_b32 s18, v239, 6
	v_lshl_add_u64 v[162:163], s[16:17], 0, v[2:3]
	v_lshl_add_u64 v[164:165], s[4:5], 0, v[0:1]
	v_lshl_add_u64 v[166:167], s[4:5], 0, v[4:5]
	v_lshl_add_u64 v[168:169], s[4:5], 0, v[6:7]
	v_mov_b32_e32 v0, v1
	v_mov_b32_e32 v2, v1
	v_mov_b32_e32 v4, v1
	v_mov_b32_e32 v6, v1
	v_mov_b32_e32 v8, v1
	v_mov_b32_e32 v10, v1
	v_mov_b32_e32 v11, v1
	v_mov_b32_e32 v12, v1
	v_mov_b32_e32 v13, v1
	v_add_u32_e32 v193, v16, v17
	v_mov_b64_e32 v[30:31], v[14:15]
	v_mov_b64_e32 v[46:47], v[14:15]
	v_cmp_gt_u32_e64 s[2:3], s2, v157
	s_mulk_i32 s12, 0x1010
	s_mov_b64 s[6:7], 0
	s_mov_b32 s13, 0x6d45000
	s_mov_b32 s15, 0x6d49000
	s_mov_b32 s16, 0x6d4a000
	s_mov_b32 s17, 0x6d4b000
	v_mov_b32_e32 v194, 0x358637bd
	s_mov_b32 s18, 0x800000
	v_mov_b64_e32 v[28:29], v[12:13]
	v_mov_b64_e32 v[26:27], v[10:11]
	v_mov_b64_e32 v[24:25], v[8:9]
	v_mov_b64_e32 v[22:23], v[6:7]
	v_mov_b64_e32 v[20:21], v[4:5]
	v_mov_b64_e32 v[18:19], v[2:3]
	v_mov_b64_e32 v[16:17], v[0:1]
	v_mov_b64_e32 v[44:45], v[12:13]
	v_mov_b64_e32 v[42:43], v[10:11]
	v_mov_b64_e32 v[40:41], v[8:9]
	v_mov_b64_e32 v[38:39], v[6:7]
	v_mov_b64_e32 v[36:37], v[4:5]
	v_mov_b64_e32 v[34:35], v[2:3]
	v_mov_b64_e32 v[32:33], v[0:1]
	s_waitcnt vmcnt(9)
	ds_write2_b64 v174, v[96:97], v[98:99] offset1:1
	s_waitcnt vmcnt(8)
	ds_write2_b64 v177, v[100:101], v[102:103] offset1:1
	s_waitcnt vmcnt(6)
	ds_write2_b64 v178, v[108:109], v[110:111] offset1:1
	ds_write2_b64 v175, v[104:105], v[106:107] offset1:1
	s_waitcnt vmcnt(5)
	ds_write2_b64 v179, v[112:113], v[114:115] offset1:1
	s_waitcnt vmcnt(4)
	ds_write2_b64 v180, v[116:117], v[118:119] offset1:1
	s_waitcnt vmcnt(3)
	ds_write2_b64 v181, v[120:121], v[122:123] offset1:1
	s_waitcnt vmcnt(2)
	ds_write2_b64 v176, v[124:125], v[126:127] offset1:1
	s_waitcnt vmcnt(1)
	ds_write2_b64 v182, v[128:129], v[130:131] offset1:1
	s_waitcnt vmcnt(0)
	ds_write2_b64 v183, v[132:133], v[134:135] offset1:1
	s_waitcnt lgkmcnt(0)
	s_barrier
	v_readlane_b32 s19, v239, 7
	v_readlane_b32 s20, v239, 8
	v_readlane_b32 s21, v239, 9
	v_readlane_b32 s22, v239, 10
	v_readlane_b32 s23, v239, 11
	v_readlane_b32 s24, v239, 12
	v_readlane_b32 s25, v239, 13
	v_readlane_b32 s26, v239, 14
	v_readlane_b32 s27, v239, 15
	v_readlane_b32 s28, v239, 16
	v_readlane_b32 s29, v239, 17
	v_readlane_b32 s30, v239, 18
	v_readlane_b32 s31, v239, 19
	s_branch .LBB0_3205
